# in-projection GEMM: 16x16x32 MFMA k-loop and hand-written epilogue (DPP row reduction for q/k head norm, exp-based tanh gelu)
# speedup vs baseline: 1.1482x; 1.0199x over previous
.Linp_epi:
	s_nop 4
	v_and_b32_e32 v64, 15, v127
	v_bfe_u32 v65, v127, 4, 2
	v_bfe_u32 v66, v127, 6, 1
	v_lshrrev_b32_e32 v67, 7, v127
	s_and_b32 s0, s38, 0x1ff
	v_lshl_add_u32 v68, v66, 6, v64
	v_add_u32_e32 v68, s0, v68
	v_lshlrev_b32_e32 v69, 6, v67
	v_lshl_add_u32 v69, v65, 2, v69
	v_add_u32_e32 v69, s37, v69
	s_lshr_b32 s1, s38, 9
	s_mov_b32 s7, 0x7060302
	s_cmp_lt_u32 s1, 2
	s_cbranch_scc1 .Lie_qk
	s_cmp_eq_u32 s1, 2
	s_cbranch_scc1 .Lie_v
	s_cmp_eq_u32 s1, 3
	s_cbranch_scc1 .Lie_xb
	v_lshlrev_b32_e32 v74, 10, v69
	v_lshl_add_u32 v74, v68, 1, v74
	s_mov_b32 s4, 0x3d372713
	s_mov_b32 s5, 0x3f4c422a
	s_mov_b32 s6, 0x4038aa3b
	v_mov_b32_e32 v80, v74
	v_mul_f32_e32 v88, s4, v0
	v_mul_f32_e32 v89, s4, v4
	v_mul_f32_e32 v90, s4, v8
	v_mul_f32_e32 v91, s4, v12
	v_mul_f32_e32 v88, v88, v0
	v_mul_f32_e32 v89, v89, v4
	v_mul_f32_e32 v90, v90, v8
	v_mul_f32_e32 v91, v91, v12
	v_mul_f32_e32 v88, v88, v0
	v_mul_f32_e32 v89, v89, v4
	v_mul_f32_e32 v90, v90, v8
	v_mul_f32_e32 v91, v91, v12
	v_add_f32_e32 v88, v0, v88
	v_add_f32_e32 v89, v4, v89
	v_add_f32_e32 v90, v8, v90
	v_add_f32_e32 v91, v12, v91
	v_mul_f32_e32 v88, s5, v88
	v_mul_f32_e32 v89, s5, v89
	v_mul_f32_e32 v90, s5, v90
	v_mul_f32_e32 v91, s5, v91
	v_mul_f32_e32 v88, s6, v88
	v_mul_f32_e32 v89, s6, v89
	v_mul_f32_e32 v90, s6, v90
	v_mul_f32_e32 v91, s6, v91
	v_exp_f32_e32 v88, v88
	v_exp_f32_e32 v89, v89
	v_exp_f32_e32 v90, v90
	v_exp_f32_e32 v91, v91
	v_mul_f32_e32 v92, 0.5, v0
	v_mul_f32_e32 v93, 0.5, v4
	v_mul_f32_e32 v94, 0.5, v8
	v_mul_f32_e32 v95, 0.5, v12
	v_add_f32_e32 v88, 1.0, v88
	v_add_f32_e32 v89, 1.0, v89
	v_add_f32_e32 v90, 1.0, v90
	v_add_f32_e32 v91, 1.0, v91
	v_rcp_f32_e32 v88, v88
	v_rcp_f32_e32 v89, v89
	v_rcp_f32_e32 v90, v90
	v_rcp_f32_e32 v91, v91
	s_nop 0
	v_fma_f32 v88, v88, -2.0, 1.0
	v_fma_f32 v89, v89, -2.0, 1.0
	v_fma_f32 v90, v90, -2.0, 1.0
	v_fma_f32 v91, v91, -2.0, 1.0
	v_add_f32_e32 v88, 1.0, v88
	v_add_f32_e32 v89, 1.0, v89
	v_add_f32_e32 v90, 1.0, v90
	v_add_f32_e32 v91, 1.0, v91
	v_mul_f32_e32 v92, v92, v88
	v_mul_f32_e32 v93, v93, v89
	v_mul_f32_e32 v94, v94, v90
	v_mul_f32_e32 v95, v95, v91
	v_bfe_u32 v88, v92, 16, 1
	v_bfe_u32 v89, v93, 16, 1
	v_bfe_u32 v90, v94, 16, 1
	v_bfe_u32 v91, v95, 16, 1
	v_add3_u32 v92, v92, v88, s33
	v_add3_u32 v93, v93, v89, s33
	v_add3_u32 v94, v94, v90, s33
	v_add3_u32 v95, v95, v91, s33
	global_store_short_d16_hi v80, v92, s[24:25] offset:0 nt
	global_store_short_d16_hi v80, v93, s[24:25] offset:32 nt
	global_store_short_d16_hi v80, v94, s[24:25] offset:64 nt
	global_store_short_d16_hi v80, v95, s[24:25] offset:96 nt
	v_add_u32_e32 v80, 0x400, v74
	v_mul_f32_e32 v88, s4, v1
	v_mul_f32_e32 v89, s4, v5
	v_mul_f32_e32 v90, s4, v9
	v_mul_f32_e32 v91, s4, v13
	v_mul_f32_e32 v88, v88, v1
	v_mul_f32_e32 v89, v89, v5
	v_mul_f32_e32 v90, v90, v9
	v_mul_f32_e32 v91, v91, v13
	v_mul_f32_e32 v88, v88, v1
	v_mul_f32_e32 v89, v89, v5
	v_mul_f32_e32 v90, v90, v9
	v_mul_f32_e32 v91, v91, v13
	v_add_f32_e32 v88, v1, v88
	v_add_f32_e32 v89, v5, v89
	v_add_f32_e32 v90, v9, v90
	v_add_f32_e32 v91, v13, v91
	v_mul_f32_e32 v88, s5, v88
	v_mul_f32_e32 v89, s5, v89
	v_mul_f32_e32 v90, s5, v90
	v_mul_f32_e32 v91, s5, v91
	v_mul_f32_e32 v88, s6, v88
	v_mul_f32_e32 v89, s6, v89
	v_mul_f32_e32 v90, s6, v90
	v_mul_f32_e32 v91, s6, v91
	v_exp_f32_e32 v88, v88
	v_exp_f32_e32 v89, v89
	v_exp_f32_e32 v90, v90
	v_exp_f32_e32 v91, v91
	v_mul_f32_e32 v92, 0.5, v1
	v_mul_f32_e32 v93, 0.5, v5
	v_mul_f32_e32 v94, 0.5, v9
	v_mul_f32_e32 v95, 0.5, v13
	v_add_f32_e32 v88, 1.0, v88
	v_add_f32_e32 v89, 1.0, v89
	v_add_f32_e32 v90, 1.0, v90
	v_add_f32_e32 v91, 1.0, v91
	v_rcp_f32_e32 v88, v88
	v_rcp_f32_e32 v89, v89
	v_rcp_f32_e32 v90, v90
	v_rcp_f32_e32 v91, v91
	s_nop 0
	v_fma_f32 v88, v88, -2.0, 1.0
	v_fma_f32 v89, v89, -2.0, 1.0
	v_fma_f32 v90, v90, -2.0, 1.0
	v_fma_f32 v91, v91, -2.0, 1.0
	v_add_f32_e32 v88, 1.0, v88
	v_add_f32_e32 v89, 1.0, v89
	v_add_f32_e32 v90, 1.0, v90
	v_add_f32_e32 v91, 1.0, v91
	v_mul_f32_e32 v92, v92, v88
	v_mul_f32_e32 v93, v93, v89
	v_mul_f32_e32 v94, v94, v90
	v_mul_f32_e32 v95, v95, v91
	v_bfe_u32 v88, v92, 16, 1
	v_bfe_u32 v89, v93, 16, 1
	v_bfe_u32 v90, v94, 16, 1
	v_bfe_u32 v91, v95, 16, 1
	v_add3_u32 v92, v92, v88, s33
	v_add3_u32 v93, v93, v89, s33
	v_add3_u32 v94, v94, v90, s33
	v_add3_u32 v95, v95, v91, s33
	global_store_short_d16_hi v80, v92, s[24:25] offset:0 nt
	global_store_short_d16_hi v80, v93, s[24:25] offset:32 nt
	global_store_short_d16_hi v80, v94, s[24:25] offset:64 nt
	global_store_short_d16_hi v80, v95, s[24:25] offset:96 nt
	v_add_u32_e32 v80, 0x800, v74
	v_mul_f32_e32 v88, s4, v2
	v_mul_f32_e32 v89, s4, v6
	v_mul_f32_e32 v90, s4, v10
	v_mul_f32_e32 v91, s4, v14
	v_mul_f32_e32 v88, v88, v2
	v_mul_f32_e32 v89, v89, v6
	v_mul_f32_e32 v90, v90, v10
	v_mul_f32_e32 v91, v91, v14
	v_mul_f32_e32 v88, v88, v2
	v_mul_f32_e32 v89, v89, v6
	v_mul_f32_e32 v90, v90, v10
	v_mul_f32_e32 v91, v91, v14
	v_add_f32_e32 v88, v2, v88
	v_add_f32_e32 v89, v6, v89
	v_add_f32_e32 v90, v10, v90
	v_add_f32_e32 v91, v14, v91
	v_mul_f32_e32 v88, s5, v88
	v_mul_f32_e32 v89, s5, v89
	v_mul_f32_e32 v90, s5, v90
	v_mul_f32_e32 v91, s5, v91
	v_mul_f32_e32 v88, s6, v88
	v_mul_f32_e32 v89, s6, v89
	v_mul_f32_e32 v90, s6, v90
	v_mul_f32_e32 v91, s6, v91
	v_exp_f32_e32 v88, v88
	v_exp_f32_e32 v89, v89
	v_exp_f32_e32 v90, v90
	v_exp_f32_e32 v91, v91
	v_mul_f32_e32 v92, 0.5, v2
	v_mul_f32_e32 v93, 0.5, v6
	v_mul_f32_e32 v94, 0.5, v10
	v_mul_f32_e32 v95, 0.5, v14
	v_add_f32_e32 v88, 1.0, v88
	v_add_f32_e32 v89, 1.0, v89
	v_add_f32_e32 v90, 1.0, v90
	v_add_f32_e32 v91, 1.0, v91
	v_rcp_f32_e32 v88, v88
	v_rcp_f32_e32 v89, v89
	v_rcp_f32_e32 v90, v90
	v_rcp_f32_e32 v91, v91
	s_nop 0
	v_fma_f32 v88, v88, -2.0, 1.0
	v_fma_f32 v89, v89, -2.0, 1.0
	v_fma_f32 v90, v90, -2.0, 1.0
	v_fma_f32 v91, v91, -2.0, 1.0
	v_add_f32_e32 v88, 1.0, v88
	v_add_f32_e32 v89, 1.0, v89
	v_add_f32_e32 v90, 1.0, v90
	v_add_f32_e32 v91, 1.0, v91
	v_mul_f32_e32 v92, v92, v88
	v_mul_f32_e32 v93, v93, v89
	v_mul_f32_e32 v94, v94, v90
	v_mul_f32_e32 v95, v95, v91
	v_bfe_u32 v88, v92, 16, 1
	v_bfe_u32 v89, v93, 16, 1
	v_bfe_u32 v90, v94, 16, 1
	v_bfe_u32 v91, v95, 16, 1
	v_add3_u32 v92, v92, v88, s33
	v_add3_u32 v93, v93, v89, s33
	v_add3_u32 v94, v94, v90, s33
	v_add3_u32 v95, v95, v91, s33
	global_store_short_d16_hi v80, v92, s[24:25] offset:0 nt
	global_store_short_d16_hi v80, v93, s[24:25] offset:32 nt
	global_store_short_d16_hi v80, v94, s[24:25] offset:64 nt
	global_store_short_d16_hi v80, v95, s[24:25] offset:96 nt
	v_add_u32_e32 v80, 0xc00, v74
	v_mul_f32_e32 v88, s4, v3
	v_mul_f32_e32 v89, s4, v7
	v_mul_f32_e32 v90, s4, v11
	v_mul_f32_e32 v91, s4, v15
	v_mul_f32_e32 v88, v88, v3
	v_mul_f32_e32 v89, v89, v7
	v_mul_f32_e32 v90, v90, v11
	v_mul_f32_e32 v91, v91, v15
	v_mul_f32_e32 v88, v88, v3
	v_mul_f32_e32 v89, v89, v7
	v_mul_f32_e32 v90, v90, v11
	v_mul_f32_e32 v91, v91, v15
	v_add_f32_e32 v88, v3, v88
	v_add_f32_e32 v89, v7, v89
	v_add_f32_e32 v90, v11, v90
	v_add_f32_e32 v91, v15, v91
	v_mul_f32_e32 v88, s5, v88
	v_mul_f32_e32 v89, s5, v89
	v_mul_f32_e32 v90, s5, v90
	v_mul_f32_e32 v91, s5, v91
	v_mul_f32_e32 v88, s6, v88
	v_mul_f32_e32 v89, s6, v89
	v_mul_f32_e32 v90, s6, v90
	v_mul_f32_e32 v91, s6, v91
	v_exp_f32_e32 v88, v88
	v_exp_f32_e32 v89, v89
	v_exp_f32_e32 v90, v90
	v_exp_f32_e32 v91, v91
	v_mul_f32_e32 v92, 0.5, v3
	v_mul_f32_e32 v93, 0.5, v7
	v_mul_f32_e32 v94, 0.5, v11
	v_mul_f32_e32 v95, 0.5, v15
	v_add_f32_e32 v88, 1.0, v88
	v_add_f32_e32 v89, 1.0, v89
	v_add_f32_e32 v90, 1.0, v90
	v_add_f32_e32 v91, 1.0, v91
	v_rcp_f32_e32 v88, v88
	v_rcp_f32_e32 v89, v89
	v_rcp_f32_e32 v90, v90
	v_rcp_f32_e32 v91, v91
	s_nop 0
	v_fma_f32 v88, v88, -2.0, 1.0
	v_fma_f32 v89, v89, -2.0, 1.0
	v_fma_f32 v90, v90, -2.0, 1.0
	v_fma_f32 v91, v91, -2.0, 1.0
	v_add_f32_e32 v88, 1.0, v88
	v_add_f32_e32 v89, 1.0, v89
	v_add_f32_e32 v90, 1.0, v90
	v_add_f32_e32 v91, 1.0, v91
	v_mul_f32_e32 v92, v92, v88
	v_mul_f32_e32 v93, v93, v89
	v_mul_f32_e32 v94, v94, v90
	v_mul_f32_e32 v95, v95, v91
	v_bfe_u32 v88, v92, 16, 1
	v_bfe_u32 v89, v93, 16, 1
	v_bfe_u32 v90, v94, 16, 1
	v_bfe_u32 v91, v95, 16, 1
	v_add3_u32 v92, v92, v88, s33
	v_add3_u32 v93, v93, v89, s33
	v_add3_u32 v94, v94, v90, s33
	v_add3_u32 v95, v95, v91, s33
	global_store_short_d16_hi v80, v92, s[24:25] offset:0 nt
	global_store_short_d16_hi v80, v93, s[24:25] offset:32 nt
	global_store_short_d16_hi v80, v94, s[24:25] offset:64 nt
	global_store_short_d16_hi v80, v95, s[24:25] offset:96 nt
	v_add_u32_e32 v80, 0x4000, v74
	v_mul_f32_e32 v88, s4, v16
	v_mul_f32_e32 v89, s4, v20
	v_mul_f32_e32 v90, s4, v24
	v_mul_f32_e32 v91, s4, v28
	v_mul_f32_e32 v88, v88, v16
	v_mul_f32_e32 v89, v89, v20
	v_mul_f32_e32 v90, v90, v24
	v_mul_f32_e32 v91, v91, v28
	v_mul_f32_e32 v88, v88, v16
	v_mul_f32_e32 v89, v89, v20
	v_mul_f32_e32 v90, v90, v24
	v_mul_f32_e32 v91, v91, v28
	v_add_f32_e32 v88, v16, v88
	v_add_f32_e32 v89, v20, v89
	v_add_f32_e32 v90, v24, v90
	v_add_f32_e32 v91, v28, v91
	v_mul_f32_e32 v88, s5, v88
	v_mul_f32_e32 v89, s5, v89
	v_mul_f32_e32 v90, s5, v90
	v_mul_f32_e32 v91, s5, v91
	v_mul_f32_e32 v88, s6, v88
	v_mul_f32_e32 v89, s6, v89
	v_mul_f32_e32 v90, s6, v90
	v_mul_f32_e32 v91, s6, v91
	v_exp_f32_e32 v88, v88
	v_exp_f32_e32 v89, v89
	v_exp_f32_e32 v90, v90
	v_exp_f32_e32 v91, v91
	v_mul_f32_e32 v92, 0.5, v16
	v_mul_f32_e32 v93, 0.5, v20
	v_mul_f32_e32 v94, 0.5, v24
	v_mul_f32_e32 v95, 0.5, v28
	v_add_f32_e32 v88, 1.0, v88
	v_add_f32_e32 v89, 1.0, v89
	v_add_f32_e32 v90, 1.0, v90
	v_add_f32_e32 v91, 1.0, v91
	v_rcp_f32_e32 v88, v88
	v_rcp_f32_e32 v89, v89
	v_rcp_f32_e32 v90, v90
	v_rcp_f32_e32 v91, v91
	s_nop 0
	v_fma_f32 v88, v88, -2.0, 1.0
	v_fma_f32 v89, v89, -2.0, 1.0
	v_fma_f32 v90, v90, -2.0, 1.0
	v_fma_f32 v91, v91, -2.0, 1.0
	v_add_f32_e32 v88, 1.0, v88
	v_add_f32_e32 v89, 1.0, v89
	v_add_f32_e32 v90, 1.0, v90
	v_add_f32_e32 v91, 1.0, v91
	v_mul_f32_e32 v92, v92, v88
	v_mul_f32_e32 v93, v93, v89
	v_mul_f32_e32 v94, v94, v90
	v_mul_f32_e32 v95, v95, v91
	v_bfe_u32 v88, v92, 16, 1
	v_bfe_u32 v89, v93, 16, 1
	v_bfe_u32 v90, v94, 16, 1
	v_bfe_u32 v91, v95, 16, 1
	v_add3_u32 v92, v92, v88, s33
	v_add3_u32 v93, v93, v89, s33
	v_add3_u32 v94, v94, v90, s33
	v_add3_u32 v95, v95, v91, s33
	global_store_short_d16_hi v80, v92, s[24:25] offset:0 nt
	global_store_short_d16_hi v80, v93, s[24:25] offset:32 nt
	global_store_short_d16_hi v80, v94, s[24:25] offset:64 nt
	global_store_short_d16_hi v80, v95, s[24:25] offset:96 nt
	v_add_u32_e32 v80, 0x4400, v74
	v_mul_f32_e32 v88, s4, v17
	v_mul_f32_e32 v89, s4, v21
	v_mul_f32_e32 v90, s4, v25
	v_mul_f32_e32 v91, s4, v29
	v_mul_f32_e32 v88, v88, v17
	v_mul_f32_e32 v89, v89, v21
	v_mul_f32_e32 v90, v90, v25
	v_mul_f32_e32 v91, v91, v29
	v_mul_f32_e32 v88, v88, v17
	v_mul_f32_e32 v89, v89, v21
	v_mul_f32_e32 v90, v90, v25
	v_mul_f32_e32 v91, v91, v29
	v_add_f32_e32 v88, v17, v88
	v_add_f32_e32 v89, v21, v89
	v_add_f32_e32 v90, v25, v90
	v_add_f32_e32 v91, v29, v91
	v_mul_f32_e32 v88, s5, v88
	v_mul_f32_e32 v89, s5, v89
	v_mul_f32_e32 v90, s5, v90
	v_mul_f32_e32 v91, s5, v91
	v_mul_f32_e32 v88, s6, v88
	v_mul_f32_e32 v89, s6, v89
	v_mul_f32_e32 v90, s6, v90
	v_mul_f32_e32 v91, s6, v91
	v_exp_f32_e32 v88, v88
	v_exp_f32_e32 v89, v89
	v_exp_f32_e32 v90, v90
	v_exp_f32_e32 v91, v91
	v_mul_f32_e32 v92, 0.5, v17
	v_mul_f32_e32 v93, 0.5, v21
	v_mul_f32_e32 v94, 0.5, v25
	v_mul_f32_e32 v95, 0.5, v29
	v_add_f32_e32 v88, 1.0, v88
	v_add_f32_e32 v89, 1.0, v89
	v_add_f32_e32 v90, 1.0, v90
	v_add_f32_e32 v91, 1.0, v91
	v_rcp_f32_e32 v88, v88
	v_rcp_f32_e32 v89, v89
	v_rcp_f32_e32 v90, v90
	v_rcp_f32_e32 v91, v91
	s_nop 0
	v_fma_f32 v88, v88, -2.0, 1.0
	v_fma_f32 v89, v89, -2.0, 1.0
	v_fma_f32 v90, v90, -2.0, 1.0
	v_fma_f32 v91, v91, -2.0, 1.0
	v_add_f32_e32 v88, 1.0, v88
	v_add_f32_e32 v89, 1.0, v89
	v_add_f32_e32 v90, 1.0, v90
	v_add_f32_e32 v91, 1.0, v91
	v_mul_f32_e32 v92, v92, v88
	v_mul_f32_e32 v93, v93, v89
	v_mul_f32_e32 v94, v94, v90
	v_mul_f32_e32 v95, v95, v91
	v_bfe_u32 v88, v92, 16, 1
	v_bfe_u32 v89, v93, 16, 1
	v_bfe_u32 v90, v94, 16, 1
	v_bfe_u32 v91, v95, 16, 1
	v_add3_u32 v92, v92, v88, s33
	v_add3_u32 v93, v93, v89, s33
	v_add3_u32 v94, v94, v90, s33
	v_add3_u32 v95, v95, v91, s33
	global_store_short_d16_hi v80, v92, s[24:25] offset:0 nt
	global_store_short_d16_hi v80, v93, s[24:25] offset:32 nt
	global_store_short_d16_hi v80, v94, s[24:25] offset:64 nt
	global_store_short_d16_hi v80, v95, s[24:25] offset:96 nt
	v_add_u32_e32 v80, 0x4800, v74
	v_mul_f32_e32 v88, s4, v18
	v_mul_f32_e32 v89, s4, v22
	v_mul_f32_e32 v90, s4, v26
	v_mul_f32_e32 v91, s4, v30
	v_mul_f32_e32 v88, v88, v18
	v_mul_f32_e32 v89, v89, v22
	v_mul_f32_e32 v90, v90, v26
	v_mul_f32_e32 v91, v91, v30
	v_mul_f32_e32 v88, v88, v18
	v_mul_f32_e32 v89, v89, v22
	v_mul_f32_e32 v90, v90, v26
	v_mul_f32_e32 v91, v91, v30
	v_add_f32_e32 v88, v18, v88
	v_add_f32_e32 v89, v22, v89
	v_add_f32_e32 v90, v26, v90
	v_add_f32_e32 v91, v30, v91
	v_mul_f32_e32 v88, s5, v88
	v_mul_f32_e32 v89, s5, v89
	v_mul_f32_e32 v90, s5, v90
	v_mul_f32_e32 v91, s5, v91
	v_mul_f32_e32 v88, s6, v88
	v_mul_f32_e32 v89, s6, v89
	v_mul_f32_e32 v90, s6, v90
	v_mul_f32_e32 v91, s6, v91
	v_exp_f32_e32 v88, v88
	v_exp_f32_e32 v89, v89
	v_exp_f32_e32 v90, v90
	v_exp_f32_e32 v91, v91
	v_mul_f32_e32 v92, 0.5, v18
	v_mul_f32_e32 v93, 0.5, v22
	v_mul_f32_e32 v94, 0.5, v26
	v_mul_f32_e32 v95, 0.5, v30
	v_add_f32_e32 v88, 1.0, v88
	v_add_f32_e32 v89, 1.0, v89
	v_add_f32_e32 v90, 1.0, v90
	v_add_f32_e32 v91, 1.0, v91
	v_rcp_f32_e32 v88, v88
	v_rcp_f32_e32 v89, v89
	v_rcp_f32_e32 v90, v90
	v_rcp_f32_e32 v91, v91
	s_nop 0
	v_fma_f32 v88, v88, -2.0, 1.0
	v_fma_f32 v89, v89, -2.0, 1.0
	v_fma_f32 v90, v90, -2.0, 1.0
	v_fma_f32 v91, v91, -2.0, 1.0
	v_add_f32_e32 v88, 1.0, v88
	v_add_f32_e32 v89, 1.0, v89
	v_add_f32_e32 v90, 1.0, v90
	v_add_f32_e32 v91, 1.0, v91
	v_mul_f32_e32 v92, v92, v88
	v_mul_f32_e32 v93, v93, v89
	v_mul_f32_e32 v94, v94, v90
	v_mul_f32_e32 v95, v95, v91
	v_bfe_u32 v88, v92, 16, 1
	v_bfe_u32 v89, v93, 16, 1
	v_bfe_u32 v90, v94, 16, 1
	v_bfe_u32 v91, v95, 16, 1
	v_add3_u32 v92, v92, v88, s33
	v_add3_u32 v93, v93, v89, s33
	v_add3_u32 v94, v94, v90, s33
	v_add3_u32 v95, v95, v91, s33
	global_store_short_d16_hi v80, v92, s[24:25] offset:0 nt
	global_store_short_d16_hi v80, v93, s[24:25] offset:32 nt
	global_store_short_d16_hi v80, v94, s[24:25] offset:64 nt
	global_store_short_d16_hi v80, v95, s[24:25] offset:96 nt
	v_add_u32_e32 v80, 0x4c00, v74
	v_mul_f32_e32 v88, s4, v19
	v_mul_f32_e32 v89, s4, v23
	v_mul_f32_e32 v90, s4, v27
	v_mul_f32_e32 v91, s4, v31
	v_mul_f32_e32 v88, v88, v19
	v_mul_f32_e32 v89, v89, v23
	v_mul_f32_e32 v90, v90, v27
	v_mul_f32_e32 v91, v91, v31
	v_mul_f32_e32 v88, v88, v19
	v_mul_f32_e32 v89, v89, v23
	v_mul_f32_e32 v90, v90, v27
	v_mul_f32_e32 v91, v91, v31
	v_add_f32_e32 v88, v19, v88
	v_add_f32_e32 v89, v23, v89
	v_add_f32_e32 v90, v27, v90
	v_add_f32_e32 v91, v31, v91
	v_mul_f32_e32 v88, s5, v88
	v_mul_f32_e32 v89, s5, v89
	v_mul_f32_e32 v90, s5, v90
	v_mul_f32_e32 v91, s5, v91
	v_mul_f32_e32 v88, s6, v88
	v_mul_f32_e32 v89, s6, v89
	v_mul_f32_e32 v90, s6, v90
	v_mul_f32_e32 v91, s6, v91
	v_exp_f32_e32 v88, v88
	v_exp_f32_e32 v89, v89
	v_exp_f32_e32 v90, v90
	v_exp_f32_e32 v91, v91
	v_mul_f32_e32 v92, 0.5, v19
	v_mul_f32_e32 v93, 0.5, v23
	v_mul_f32_e32 v94, 0.5, v27
	v_mul_f32_e32 v95, 0.5, v31
	v_add_f32_e32 v88, 1.0, v88
	v_add_f32_e32 v89, 1.0, v89
	v_add_f32_e32 v90, 1.0, v90
	v_add_f32_e32 v91, 1.0, v91
	v_rcp_f32_e32 v88, v88
	v_rcp_f32_e32 v89, v89
	v_rcp_f32_e32 v90, v90
	v_rcp_f32_e32 v91, v91
	s_nop 0
	v_fma_f32 v88, v88, -2.0, 1.0
	v_fma_f32 v89, v89, -2.0, 1.0
	v_fma_f32 v90, v90, -2.0, 1.0
	v_fma_f32 v91, v91, -2.0, 1.0
	v_add_f32_e32 v88, 1.0, v88
	v_add_f32_e32 v89, 1.0, v89
	v_add_f32_e32 v90, 1.0, v90
	v_add_f32_e32 v91, 1.0, v91
	v_mul_f32_e32 v92, v92, v88
	v_mul_f32_e32 v93, v93, v89
	v_mul_f32_e32 v94, v94, v90
	v_mul_f32_e32 v95, v95, v91
	v_bfe_u32 v88, v92, 16, 1
	v_bfe_u32 v89, v93, 16, 1
	v_bfe_u32 v90, v94, 16, 1
	v_bfe_u32 v91, v95, 16, 1
	v_add3_u32 v92, v92, v88, s33
	v_add3_u32 v93, v93, v89, s33
	v_add3_u32 v94, v94, v90, s33
	v_add3_u32 v95, v95, v91, s33
	global_store_short_d16_hi v80, v92, s[24:25] offset:0 nt
	global_store_short_d16_hi v80, v93, s[24:25] offset:32 nt
	global_store_short_d16_hi v80, v94, s[24:25] offset:64 nt
	global_store_short_d16_hi v80, v95, s[24:25] offset:96 nt
	v_add_u32_e32 v80, 0x8000, v74
	v_mul_f32_e32 v88, s4, v32
	v_mul_f32_e32 v89, s4, v36
	v_mul_f32_e32 v90, s4, v40
	v_mul_f32_e32 v91, s4, v44
	v_mul_f32_e32 v88, v88, v32
	v_mul_f32_e32 v89, v89, v36
	v_mul_f32_e32 v90, v90, v40
	v_mul_f32_e32 v91, v91, v44
	v_mul_f32_e32 v88, v88, v32
	v_mul_f32_e32 v89, v89, v36
	v_mul_f32_e32 v90, v90, v40
	v_mul_f32_e32 v91, v91, v44
	v_add_f32_e32 v88, v32, v88
	v_add_f32_e32 v89, v36, v89
	v_add_f32_e32 v90, v40, v90
	v_add_f32_e32 v91, v44, v91
	v_mul_f32_e32 v88, s5, v88
	v_mul_f32_e32 v89, s5, v89
	v_mul_f32_e32 v90, s5, v90
	v_mul_f32_e32 v91, s5, v91
	v_mul_f32_e32 v88, s6, v88
	v_mul_f32_e32 v89, s6, v89
	v_mul_f32_e32 v90, s6, v90
	v_mul_f32_e32 v91, s6, v91
	v_exp_f32_e32 v88, v88
	v_exp_f32_e32 v89, v89
	v_exp_f32_e32 v90, v90
	v_exp_f32_e32 v91, v91
	v_mul_f32_e32 v92, 0.5, v32
	v_mul_f32_e32 v93, 0.5, v36
	v_mul_f32_e32 v94, 0.5, v40
	v_mul_f32_e32 v95, 0.5, v44
	v_add_f32_e32 v88, 1.0, v88
	v_add_f32_e32 v89, 1.0, v89
	v_add_f32_e32 v90, 1.0, v90
	v_add_f32_e32 v91, 1.0, v91
	v_rcp_f32_e32 v88, v88
	v_rcp_f32_e32 v89, v89
	v_rcp_f32_e32 v90, v90
	v_rcp_f32_e32 v91, v91
	s_nop 0
	v_fma_f32 v88, v88, -2.0, 1.0
	v_fma_f32 v89, v89, -2.0, 1.0
	v_fma_f32 v90, v90, -2.0, 1.0
	v_fma_f32 v91, v91, -2.0, 1.0
	v_add_f32_e32 v88, 1.0, v88
	v_add_f32_e32 v89, 1.0, v89
	v_add_f32_e32 v90, 1.0, v90
	v_add_f32_e32 v91, 1.0, v91
	v_mul_f32_e32 v92, v92, v88
	v_mul_f32_e32 v93, v93, v89
	v_mul_f32_e32 v94, v94, v90
	v_mul_f32_e32 v95, v95, v91
	v_bfe_u32 v88, v92, 16, 1
	v_bfe_u32 v89, v93, 16, 1
	v_bfe_u32 v90, v94, 16, 1
	v_bfe_u32 v91, v95, 16, 1
	v_add3_u32 v92, v92, v88, s33
	v_add3_u32 v93, v93, v89, s33
	v_add3_u32 v94, v94, v90, s33
	v_add3_u32 v95, v95, v91, s33
	global_store_short_d16_hi v80, v92, s[24:25] offset:0 nt
	global_store_short_d16_hi v80, v93, s[24:25] offset:32 nt
	global_store_short_d16_hi v80, v94, s[24:25] offset:64 nt
	global_store_short_d16_hi v80, v95, s[24:25] offset:96 nt
	v_add_u32_e32 v80, 0x8400, v74
	v_mul_f32_e32 v88, s4, v33
	v_mul_f32_e32 v89, s4, v37
	v_mul_f32_e32 v90, s4, v41
	v_mul_f32_e32 v91, s4, v45
	v_mul_f32_e32 v88, v88, v33
	v_mul_f32_e32 v89, v89, v37
	v_mul_f32_e32 v90, v90, v41
	v_mul_f32_e32 v91, v91, v45
	v_mul_f32_e32 v88, v88, v33
	v_mul_f32_e32 v89, v89, v37
	v_mul_f32_e32 v90, v90, v41
	v_mul_f32_e32 v91, v91, v45
	v_add_f32_e32 v88, v33, v88
	v_add_f32_e32 v89, v37, v89
	v_add_f32_e32 v90, v41, v90
	v_add_f32_e32 v91, v45, v91
	v_mul_f32_e32 v88, s5, v88
	v_mul_f32_e32 v89, s5, v89
	v_mul_f32_e32 v90, s5, v90
	v_mul_f32_e32 v91, s5, v91
	v_mul_f32_e32 v88, s6, v88
	v_mul_f32_e32 v89, s6, v89
	v_mul_f32_e32 v90, s6, v90
	v_mul_f32_e32 v91, s6, v91
	v_exp_f32_e32 v88, v88
	v_exp_f32_e32 v89, v89
	v_exp_f32_e32 v90, v90
	v_exp_f32_e32 v91, v91
	v_mul_f32_e32 v92, 0.5, v33
	v_mul_f32_e32 v93, 0.5, v37
	v_mul_f32_e32 v94, 0.5, v41
	v_mul_f32_e32 v95, 0.5, v45
	v_add_f32_e32 v88, 1.0, v88
	v_add_f32_e32 v89, 1.0, v89
	v_add_f32_e32 v90, 1.0, v90
	v_add_f32_e32 v91, 1.0, v91
	v_rcp_f32_e32 v88, v88
	v_rcp_f32_e32 v89, v89
	v_rcp_f32_e32 v90, v90
	v_rcp_f32_e32 v91, v91
	s_nop 0
	v_fma_f32 v88, v88, -2.0, 1.0
	v_fma_f32 v89, v89, -2.0, 1.0
	v_fma_f32 v90, v90, -2.0, 1.0
	v_fma_f32 v91, v91, -2.0, 1.0
	v_add_f32_e32 v88, 1.0, v88
	v_add_f32_e32 v89, 1.0, v89
	v_add_f32_e32 v90, 1.0, v90
	v_add_f32_e32 v91, 1.0, v91
	v_mul_f32_e32 v92, v92, v88
	v_mul_f32_e32 v93, v93, v89
	v_mul_f32_e32 v94, v94, v90
	v_mul_f32_e32 v95, v95, v91
	v_bfe_u32 v88, v92, 16, 1
	v_bfe_u32 v89, v93, 16, 1
	v_bfe_u32 v90, v94, 16, 1
	v_bfe_u32 v91, v95, 16, 1
	v_add3_u32 v92, v92, v88, s33
	v_add3_u32 v93, v93, v89, s33
	v_add3_u32 v94, v94, v90, s33
	v_add3_u32 v95, v95, v91, s33
	global_store_short_d16_hi v80, v92, s[24:25] offset:0 nt
	global_store_short_d16_hi v80, v93, s[24:25] offset:32 nt
	global_store_short_d16_hi v80, v94, s[24:25] offset:64 nt
	global_store_short_d16_hi v80, v95, s[24:25] offset:96 nt
	v_add_u32_e32 v80, 0x8800, v74
	v_mul_f32_e32 v88, s4, v34
	v_mul_f32_e32 v89, s4, v38
	v_mul_f32_e32 v90, s4, v42
	v_mul_f32_e32 v91, s4, v46
	v_mul_f32_e32 v88, v88, v34
	v_mul_f32_e32 v89, v89, v38
	v_mul_f32_e32 v90, v90, v42
	v_mul_f32_e32 v91, v91, v46
	v_mul_f32_e32 v88, v88, v34
	v_mul_f32_e32 v89, v89, v38
	v_mul_f32_e32 v90, v90, v42
	v_mul_f32_e32 v91, v91, v46
	v_add_f32_e32 v88, v34, v88
	v_add_f32_e32 v89, v38, v89
	v_add_f32_e32 v90, v42, v90
	v_add_f32_e32 v91, v46, v91
	v_mul_f32_e32 v88, s5, v88
	v_mul_f32_e32 v89, s5, v89
	v_mul_f32_e32 v90, s5, v90
	v_mul_f32_e32 v91, s5, v91
	v_mul_f32_e32 v88, s6, v88
	v_mul_f32_e32 v89, s6, v89
	v_mul_f32_e32 v90, s6, v90
	v_mul_f32_e32 v91, s6, v91
	v_exp_f32_e32 v88, v88
	v_exp_f32_e32 v89, v89
	v_exp_f32_e32 v90, v90
	v_exp_f32_e32 v91, v91
	v_mul_f32_e32 v92, 0.5, v34
	v_mul_f32_e32 v93, 0.5, v38
	v_mul_f32_e32 v94, 0.5, v42
	v_mul_f32_e32 v95, 0.5, v46
	v_add_f32_e32 v88, 1.0, v88
	v_add_f32_e32 v89, 1.0, v89
	v_add_f32_e32 v90, 1.0, v90
	v_add_f32_e32 v91, 1.0, v91
	v_rcp_f32_e32 v88, v88
	v_rcp_f32_e32 v89, v89
	v_rcp_f32_e32 v90, v90
	v_rcp_f32_e32 v91, v91
	s_nop 0
	v_fma_f32 v88, v88, -2.0, 1.0
	v_fma_f32 v89, v89, -2.0, 1.0
	v_fma_f32 v90, v90, -2.0, 1.0
	v_fma_f32 v91, v91, -2.0, 1.0
	v_add_f32_e32 v88, 1.0, v88
	v_add_f32_e32 v89, 1.0, v89
	v_add_f32_e32 v90, 1.0, v90
	v_add_f32_e32 v91, 1.0, v91
	v_mul_f32_e32 v92, v92, v88
	v_mul_f32_e32 v93, v93, v89
	v_mul_f32_e32 v94, v94, v90
	v_mul_f32_e32 v95, v95, v91
	v_bfe_u32 v88, v92, 16, 1
	v_bfe_u32 v89, v93, 16, 1
	v_bfe_u32 v90, v94, 16, 1
	v_bfe_u32 v91, v95, 16, 1
	v_add3_u32 v92, v92, v88, s33
	v_add3_u32 v93, v93, v89, s33
	v_add3_u32 v94, v94, v90, s33
	v_add3_u32 v95, v95, v91, s33
	global_store_short_d16_hi v80, v92, s[24:25] offset:0 nt
	global_store_short_d16_hi v80, v93, s[24:25] offset:32 nt
	global_store_short_d16_hi v80, v94, s[24:25] offset:64 nt
	global_store_short_d16_hi v80, v95, s[24:25] offset:96 nt
	v_add_u32_e32 v80, 0x8c00, v74
	v_mul_f32_e32 v88, s4, v35
	v_mul_f32_e32 v89, s4, v39
	v_mul_f32_e32 v90, s4, v43
	v_mul_f32_e32 v91, s4, v47
	v_mul_f32_e32 v88, v88, v35
	v_mul_f32_e32 v89, v89, v39
	v_mul_f32_e32 v90, v90, v43
	v_mul_f32_e32 v91, v91, v47
	v_mul_f32_e32 v88, v88, v35
	v_mul_f32_e32 v89, v89, v39
	v_mul_f32_e32 v90, v90, v43
	v_mul_f32_e32 v91, v91, v47
	v_add_f32_e32 v88, v35, v88
	v_add_f32_e32 v89, v39, v89
	v_add_f32_e32 v90, v43, v90
	v_add_f32_e32 v91, v47, v91
	v_mul_f32_e32 v88, s5, v88
	v_mul_f32_e32 v89, s5, v89
	v_mul_f32_e32 v90, s5, v90
	v_mul_f32_e32 v91, s5, v91
	v_mul_f32_e32 v88, s6, v88
	v_mul_f32_e32 v89, s6, v89
	v_mul_f32_e32 v90, s6, v90
	v_mul_f32_e32 v91, s6, v91
	v_exp_f32_e32 v88, v88
	v_exp_f32_e32 v89, v89
	v_exp_f32_e32 v90, v90
	v_exp_f32_e32 v91, v91
	v_mul_f32_e32 v92, 0.5, v35
	v_mul_f32_e32 v93, 0.5, v39
	v_mul_f32_e32 v94, 0.5, v43
	v_mul_f32_e32 v95, 0.5, v47
	v_add_f32_e32 v88, 1.0, v88
	v_add_f32_e32 v89, 1.0, v89
	v_add_f32_e32 v90, 1.0, v90
	v_add_f32_e32 v91, 1.0, v91
	v_rcp_f32_e32 v88, v88
	v_rcp_f32_e32 v89, v89
	v_rcp_f32_e32 v90, v90
	v_rcp_f32_e32 v91, v91
	s_nop 0
	v_fma_f32 v88, v88, -2.0, 1.0
	v_fma_f32 v89, v89, -2.0, 1.0
	v_fma_f32 v90, v90, -2.0, 1.0
	v_fma_f32 v91, v91, -2.0, 1.0
	v_add_f32_e32 v88, 1.0, v88
	v_add_f32_e32 v89, 1.0, v89
	v_add_f32_e32 v90, 1.0, v90
	v_add_f32_e32 v91, 1.0, v91
	v_mul_f32_e32 v92, v92, v88
	v_mul_f32_e32 v93, v93, v89
	v_mul_f32_e32 v94, v94, v90
	v_mul_f32_e32 v95, v95, v91
	v_bfe_u32 v88, v92, 16, 1
	v_bfe_u32 v89, v93, 16, 1
	v_bfe_u32 v90, v94, 16, 1
	v_bfe_u32 v91, v95, 16, 1
	v_add3_u32 v92, v92, v88, s33
	v_add3_u32 v93, v93, v89, s33
	v_add3_u32 v94, v94, v90, s33
	v_add3_u32 v95, v95, v91, s33
	global_store_short_d16_hi v80, v92, s[24:25] offset:0 nt
	global_store_short_d16_hi v80, v93, s[24:25] offset:32 nt
	global_store_short_d16_hi v80, v94, s[24:25] offset:64 nt
	global_store_short_d16_hi v80, v95, s[24:25] offset:96 nt
	v_add_u32_e32 v80, 0xc000, v74
	v_mul_f32_e32 v88, s4, v48
	v_mul_f32_e32 v89, s4, v52
	v_mul_f32_e32 v90, s4, v56
	v_mul_f32_e32 v91, s4, v60
	v_mul_f32_e32 v88, v88, v48
	v_mul_f32_e32 v89, v89, v52
	v_mul_f32_e32 v90, v90, v56
	v_mul_f32_e32 v91, v91, v60
	v_mul_f32_e32 v88, v88, v48
	v_mul_f32_e32 v89, v89, v52
	v_mul_f32_e32 v90, v90, v56
	v_mul_f32_e32 v91, v91, v60
	v_add_f32_e32 v88, v48, v88
	v_add_f32_e32 v89, v52, v89
	v_add_f32_e32 v90, v56, v90
	v_add_f32_e32 v91, v60, v91
	v_mul_f32_e32 v88, s5, v88
	v_mul_f32_e32 v89, s5, v89
	v_mul_f32_e32 v90, s5, v90
	v_mul_f32_e32 v91, s5, v91
	v_mul_f32_e32 v88, s6, v88
	v_mul_f32_e32 v89, s6, v89
	v_mul_f32_e32 v90, s6, v90
	v_mul_f32_e32 v91, s6, v91
	v_exp_f32_e32 v88, v88
	v_exp_f32_e32 v89, v89
	v_exp_f32_e32 v90, v90
	v_exp_f32_e32 v91, v91
	v_mul_f32_e32 v92, 0.5, v48
	v_mul_f32_e32 v93, 0.5, v52
	v_mul_f32_e32 v94, 0.5, v56
	v_mul_f32_e32 v95, 0.5, v60
	v_add_f32_e32 v88, 1.0, v88
	v_add_f32_e32 v89, 1.0, v89
	v_add_f32_e32 v90, 1.0, v90
	v_add_f32_e32 v91, 1.0, v91
	v_rcp_f32_e32 v88, v88
	v_rcp_f32_e32 v89, v89
	v_rcp_f32_e32 v90, v90
	v_rcp_f32_e32 v91, v91
	s_nop 0
	v_fma_f32 v88, v88, -2.0, 1.0
	v_fma_f32 v89, v89, -2.0, 1.0
	v_fma_f32 v90, v90, -2.0, 1.0
	v_fma_f32 v91, v91, -2.0, 1.0
	v_add_f32_e32 v88, 1.0, v88
	v_add_f32_e32 v89, 1.0, v89
	v_add_f32_e32 v90, 1.0, v90
	v_add_f32_e32 v91, 1.0, v91
	v_mul_f32_e32 v92, v92, v88
	v_mul_f32_e32 v93, v93, v89
	v_mul_f32_e32 v94, v94, v90
	v_mul_f32_e32 v95, v95, v91
	v_bfe_u32 v88, v92, 16, 1
	v_bfe_u32 v89, v93, 16, 1
	v_bfe_u32 v90, v94, 16, 1
	v_bfe_u32 v91, v95, 16, 1
	v_add3_u32 v92, v92, v88, s33
	v_add3_u32 v93, v93, v89, s33
	v_add3_u32 v94, v94, v90, s33
	v_add3_u32 v95, v95, v91, s33
	global_store_short_d16_hi v80, v92, s[24:25] offset:0 nt
	global_store_short_d16_hi v80, v93, s[24:25] offset:32 nt
	global_store_short_d16_hi v80, v94, s[24:25] offset:64 nt
	global_store_short_d16_hi v80, v95, s[24:25] offset:96 nt
	v_add_u32_e32 v80, 0xc400, v74
	v_mul_f32_e32 v88, s4, v49
	v_mul_f32_e32 v89, s4, v53
	v_mul_f32_e32 v90, s4, v57
	v_mul_f32_e32 v91, s4, v61
	v_mul_f32_e32 v88, v88, v49
	v_mul_f32_e32 v89, v89, v53
	v_mul_f32_e32 v90, v90, v57
	v_mul_f32_e32 v91, v91, v61
	v_mul_f32_e32 v88, v88, v49
	v_mul_f32_e32 v89, v89, v53
	v_mul_f32_e32 v90, v90, v57
	v_mul_f32_e32 v91, v91, v61
	v_add_f32_e32 v88, v49, v88
	v_add_f32_e32 v89, v53, v89
	v_add_f32_e32 v90, v57, v90
	v_add_f32_e32 v91, v61, v91
	v_mul_f32_e32 v88, s5, v88
	v_mul_f32_e32 v89, s5, v89
	v_mul_f32_e32 v90, s5, v90
	v_mul_f32_e32 v91, s5, v91
	v_mul_f32_e32 v88, s6, v88
	v_mul_f32_e32 v89, s6, v89
	v_mul_f32_e32 v90, s6, v90
	v_mul_f32_e32 v91, s6, v91
	v_exp_f32_e32 v88, v88
	v_exp_f32_e32 v89, v89
	v_exp_f32_e32 v90, v90
	v_exp_f32_e32 v91, v91
	v_mul_f32_e32 v92, 0.5, v49
	v_mul_f32_e32 v93, 0.5, v53
	v_mul_f32_e32 v94, 0.5, v57
	v_mul_f32_e32 v95, 0.5, v61
	v_add_f32_e32 v88, 1.0, v88
	v_add_f32_e32 v89, 1.0, v89
	v_add_f32_e32 v90, 1.0, v90
	v_add_f32_e32 v91, 1.0, v91
	v_rcp_f32_e32 v88, v88
	v_rcp_f32_e32 v89, v89
	v_rcp_f32_e32 v90, v90
	v_rcp_f32_e32 v91, v91
	s_nop 0
	v_fma_f32 v88, v88, -2.0, 1.0
	v_fma_f32 v89, v89, -2.0, 1.0
	v_fma_f32 v90, v90, -2.0, 1.0
	v_fma_f32 v91, v91, -2.0, 1.0
	v_add_f32_e32 v88, 1.0, v88
	v_add_f32_e32 v89, 1.0, v89
	v_add_f32_e32 v90, 1.0, v90
	v_add_f32_e32 v91, 1.0, v91
	v_mul_f32_e32 v92, v92, v88
	v_mul_f32_e32 v93, v93, v89
	v_mul_f32_e32 v94, v94, v90
	v_mul_f32_e32 v95, v95, v91
	v_bfe_u32 v88, v92, 16, 1
	v_bfe_u32 v89, v93, 16, 1
	v_bfe_u32 v90, v94, 16, 1
	v_bfe_u32 v91, v95, 16, 1
	v_add3_u32 v92, v92, v88, s33
	v_add3_u32 v93, v93, v89, s33
	v_add3_u32 v94, v94, v90, s33
	v_add3_u32 v95, v95, v91, s33
	global_store_short_d16_hi v80, v92, s[24:25] offset:0 nt
	global_store_short_d16_hi v80, v93, s[24:25] offset:32 nt
	global_store_short_d16_hi v80, v94, s[24:25] offset:64 nt
	global_store_short_d16_hi v80, v95, s[24:25] offset:96 nt
	v_add_u32_e32 v80, 0xc800, v74
	v_mul_f32_e32 v88, s4, v50
	v_mul_f32_e32 v89, s4, v54
	v_mul_f32_e32 v90, s4, v58
	v_mul_f32_e32 v91, s4, v62
	v_mul_f32_e32 v88, v88, v50
	v_mul_f32_e32 v89, v89, v54
	v_mul_f32_e32 v90, v90, v58
	v_mul_f32_e32 v91, v91, v62
	v_mul_f32_e32 v88, v88, v50
	v_mul_f32_e32 v89, v89, v54
	v_mul_f32_e32 v90, v90, v58
	v_mul_f32_e32 v91, v91, v62
	v_add_f32_e32 v88, v50, v88
	v_add_f32_e32 v89, v54, v89
	v_add_f32_e32 v90, v58, v90
	v_add_f32_e32 v91, v62, v91
	v_mul_f32_e32 v88, s5, v88
	v_mul_f32_e32 v89, s5, v89
	v_mul_f32_e32 v90, s5, v90
	v_mul_f32_e32 v91, s5, v91
	v_mul_f32_e32 v88, s6, v88
	v_mul_f32_e32 v89, s6, v89
	v_mul_f32_e32 v90, s6, v90
	v_mul_f32_e32 v91, s6, v91
	v_exp_f32_e32 v88, v88
	v_exp_f32_e32 v89, v89
	v_exp_f32_e32 v90, v90
	v_exp_f32_e32 v91, v91
	v_mul_f32_e32 v92, 0.5, v50
	v_mul_f32_e32 v93, 0.5, v54
	v_mul_f32_e32 v94, 0.5, v58
	v_mul_f32_e32 v95, 0.5, v62
	v_add_f32_e32 v88, 1.0, v88
	v_add_f32_e32 v89, 1.0, v89
	v_add_f32_e32 v90, 1.0, v90
	v_add_f32_e32 v91, 1.0, v91
	v_rcp_f32_e32 v88, v88
	v_rcp_f32_e32 v89, v89
	v_rcp_f32_e32 v90, v90
	v_rcp_f32_e32 v91, v91
	s_nop 0
	v_fma_f32 v88, v88, -2.0, 1.0
	v_fma_f32 v89, v89, -2.0, 1.0
	v_fma_f32 v90, v90, -2.0, 1.0
	v_fma_f32 v91, v91, -2.0, 1.0
	v_add_f32_e32 v88, 1.0, v88
	v_add_f32_e32 v89, 1.0, v89
	v_add_f32_e32 v90, 1.0, v90
	v_add_f32_e32 v91, 1.0, v91
	v_mul_f32_e32 v92, v92, v88
	v_mul_f32_e32 v93, v93, v89
	v_mul_f32_e32 v94, v94, v90
	v_mul_f32_e32 v95, v95, v91
	v_bfe_u32 v88, v92, 16, 1
	v_bfe_u32 v89, v93, 16, 1
	v_bfe_u32 v90, v94, 16, 1
	v_bfe_u32 v91, v95, 16, 1
	v_add3_u32 v92, v92, v88, s33
	v_add3_u32 v93, v93, v89, s33
	v_add3_u32 v94, v94, v90, s33
	v_add3_u32 v95, v95, v91, s33
	global_store_short_d16_hi v80, v92, s[24:25] offset:0 nt
	global_store_short_d16_hi v80, v93, s[24:25] offset:32 nt
	global_store_short_d16_hi v80, v94, s[24:25] offset:64 nt
	global_store_short_d16_hi v80, v95, s[24:25] offset:96 nt
	v_add_u32_e32 v80, 0xcc00, v74
	v_mul_f32_e32 v88, s4, v51
	v_mul_f32_e32 v89, s4, v55
	v_mul_f32_e32 v90, s4, v59
	v_mul_f32_e32 v91, s4, v63
	v_mul_f32_e32 v88, v88, v51
	v_mul_f32_e32 v89, v89, v55
	v_mul_f32_e32 v90, v90, v59
	v_mul_f32_e32 v91, v91, v63
	v_mul_f32_e32 v88, v88, v51
	v_mul_f32_e32 v89, v89, v55
	v_mul_f32_e32 v90, v90, v59
	v_mul_f32_e32 v91, v91, v63
	v_add_f32_e32 v88, v51, v88
	v_add_f32_e32 v89, v55, v89
	v_add_f32_e32 v90, v59, v90
	v_add_f32_e32 v91, v63, v91
	v_mul_f32_e32 v88, s5, v88
	v_mul_f32_e32 v89, s5, v89
	v_mul_f32_e32 v90, s5, v90
	v_mul_f32_e32 v91, s5, v91
	v_mul_f32_e32 v88, s6, v88
	v_mul_f32_e32 v89, s6, v89
	v_mul_f32_e32 v90, s6, v90
	v_mul_f32_e32 v91, s6, v91
	v_exp_f32_e32 v88, v88
	v_exp_f32_e32 v89, v89
	v_exp_f32_e32 v90, v90
	v_exp_f32_e32 v91, v91
	v_mul_f32_e32 v92, 0.5, v51
	v_mul_f32_e32 v93, 0.5, v55
	v_mul_f32_e32 v94, 0.5, v59
	v_mul_f32_e32 v95, 0.5, v63
	v_add_f32_e32 v88, 1.0, v88
	v_add_f32_e32 v89, 1.0, v89
	v_add_f32_e32 v90, 1.0, v90
	v_add_f32_e32 v91, 1.0, v91
	v_rcp_f32_e32 v88, v88
	v_rcp_f32_e32 v89, v89
	v_rcp_f32_e32 v90, v90
	v_rcp_f32_e32 v91, v91
	s_nop 0
	v_fma_f32 v88, v88, -2.0, 1.0
	v_fma_f32 v89, v89, -2.0, 1.0
	v_fma_f32 v90, v90, -2.0, 1.0
	v_fma_f32 v91, v91, -2.0, 1.0
	v_add_f32_e32 v88, 1.0, v88
	v_add_f32_e32 v89, 1.0, v89
	v_add_f32_e32 v90, 1.0, v90
	v_add_f32_e32 v91, 1.0, v91
	v_mul_f32_e32 v92, v92, v88
	v_mul_f32_e32 v93, v93, v89
	v_mul_f32_e32 v94, v94, v90
	v_mul_f32_e32 v95, v95, v91
	v_bfe_u32 v88, v92, 16, 1
	v_bfe_u32 v89, v93, 16, 1
	v_bfe_u32 v90, v94, 16, 1
	v_bfe_u32 v91, v95, 16, 1
	v_add3_u32 v92, v92, v88, s33
	v_add3_u32 v93, v93, v89, s33
	v_add3_u32 v94, v94, v90, s33
	v_add3_u32 v95, v95, v91, s33
	global_store_short_d16_hi v80, v92, s[24:25] offset:0 nt
	global_store_short_d16_hi v80, v93, s[24:25] offset:32 nt
	global_store_short_d16_hi v80, v94, s[24:25] offset:64 nt
	global_store_short_d16_hi v80, v95, s[24:25] offset:96 nt
	s_branch .Lie_done
.Lie_xb:
	v_lshlrev_b32_e32 v75, 11, v69
	v_lshl_add_u32 v75, v68, 2, v75
	v_mov_b32_e32 v80, v75
	global_store_dword v80, v0, s[26:27] offset:0 nt
	global_store_dword v80, v4, s[26:27] offset:64 nt
	global_store_dword v80, v8, s[26:27] offset:128 nt
	global_store_dword v80, v12, s[26:27] offset:192 nt
	v_add_u32_e32 v81, 0x800, v75
	global_store_dword v81, v1, s[26:27] offset:0 nt
	global_store_dword v81, v5, s[26:27] offset:64 nt
	global_store_dword v81, v9, s[26:27] offset:128 nt
	global_store_dword v81, v13, s[26:27] offset:192 nt
	v_add_u32_e32 v82, 0x1000, v75
	global_store_dword v82, v2, s[26:27] offset:0 nt
	global_store_dword v82, v6, s[26:27] offset:64 nt
	global_store_dword v82, v10, s[26:27] offset:128 nt
	global_store_dword v82, v14, s[26:27] offset:192 nt
	v_add_u32_e32 v83, 0x1800, v75
	global_store_dword v83, v3, s[26:27] offset:0 nt
	global_store_dword v83, v7, s[26:27] offset:64 nt
	global_store_dword v83, v11, s[26:27] offset:128 nt
	global_store_dword v83, v15, s[26:27] offset:192 nt
	v_add_u32_e32 v80, 0x8000, v75
	global_store_dword v80, v16, s[26:27] offset:0 nt
	global_store_dword v80, v20, s[26:27] offset:64 nt
	global_store_dword v80, v24, s[26:27] offset:128 nt
	global_store_dword v80, v28, s[26:27] offset:192 nt
	v_add_u32_e32 v81, 0x8800, v75
	global_store_dword v81, v17, s[26:27] offset:0 nt
	global_store_dword v81, v21, s[26:27] offset:64 nt
	global_store_dword v81, v25, s[26:27] offset:128 nt
	global_store_dword v81, v29, s[26:27] offset:192 nt
	v_add_u32_e32 v82, 0x9000, v75
	global_store_dword v82, v18, s[26:27] offset:0 nt
	global_store_dword v82, v22, s[26:27] offset:64 nt
	global_store_dword v82, v26, s[26:27] offset:128 nt
	global_store_dword v82, v30, s[26:27] offset:192 nt
	v_add_u32_e32 v83, 0x9800, v75
	global_store_dword v83, v19, s[26:27] offset:0 nt
	global_store_dword v83, v23, s[26:27] offset:64 nt
	global_store_dword v83, v27, s[26:27] offset:128 nt
	global_store_dword v83, v31, s[26:27] offset:192 nt
	v_add_u32_e32 v80, 0x10000, v75
	global_store_dword v80, v32, s[26:27] offset:0 nt
	global_store_dword v80, v36, s[26:27] offset:64 nt
	global_store_dword v80, v40, s[26:27] offset:128 nt
	global_store_dword v80, v44, s[26:27] offset:192 nt
	v_add_u32_e32 v81, 0x10800, v75
	global_store_dword v81, v33, s[26:27] offset:0 nt
	global_store_dword v81, v37, s[26:27] offset:64 nt
	global_store_dword v81, v41, s[26:27] offset:128 nt
	global_store_dword v81, v45, s[26:27] offset:192 nt
	v_add_u32_e32 v82, 0x11000, v75
	global_store_dword v82, v34, s[26:27] offset:0 nt
	global_store_dword v82, v38, s[26:27] offset:64 nt
	global_store_dword v82, v42, s[26:27] offset:128 nt
	global_store_dword v82, v46, s[26:27] offset:192 nt
	v_add_u32_e32 v83, 0x11800, v75
	global_store_dword v83, v35, s[26:27] offset:0 nt
	global_store_dword v83, v39, s[26:27] offset:64 nt
	global_store_dword v83, v43, s[26:27] offset:128 nt
	global_store_dword v83, v47, s[26:27] offset:192 nt
	v_add_u32_e32 v80, 0x18000, v75
	global_store_dword v80, v48, s[26:27] offset:0 nt
	global_store_dword v80, v52, s[26:27] offset:64 nt
	global_store_dword v80, v56, s[26:27] offset:128 nt
	global_store_dword v80, v60, s[26:27] offset:192 nt
	v_add_u32_e32 v81, 0x18800, v75
	global_store_dword v81, v49, s[26:27] offset:0 nt
	global_store_dword v81, v53, s[26:27] offset:64 nt
	global_store_dword v81, v57, s[26:27] offset:128 nt
	global_store_dword v81, v61, s[26:27] offset:192 nt
	v_add_u32_e32 v82, 0x19000, v75
	global_store_dword v82, v50, s[26:27] offset:0 nt
	global_store_dword v82, v54, s[26:27] offset:64 nt
	global_store_dword v82, v58, s[26:27] offset:128 nt
	global_store_dword v82, v62, s[26:27] offset:192 nt
	v_add_u32_e32 v83, 0x19800, v75
	global_store_dword v83, v51, s[26:27] offset:0 nt
	global_store_dword v83, v55, s[26:27] offset:64 nt
	global_store_dword v83, v59, s[26:27] offset:128 nt
	global_store_dword v83, v63, s[26:27] offset:192 nt
	s_branch .Lie_done
.Lie_v:
	s_cmpk_ge_u32 s37, 0x1000
	s_cbranch_scc1 .Lie_v_nocache
	v_lshlrev_b32_e32 v75, 11, v69
	v_lshl_add_u32 v75, v68, 2, v75
	v_mov_b32_e32 v80, v75
	global_store_dword v80, v0, s[8:9] offset:0 nt
	global_store_dword v80, v4, s[8:9] offset:64 nt
	global_store_dword v80, v8, s[8:9] offset:128 nt
	global_store_dword v80, v12, s[8:9] offset:192 nt
	v_add_u32_e32 v81, 0x800, v75
	global_store_dword v81, v1, s[8:9] offset:0 nt
	global_store_dword v81, v5, s[8:9] offset:64 nt
	global_store_dword v81, v9, s[8:9] offset:128 nt
	global_store_dword v81, v13, s[8:9] offset:192 nt
	v_add_u32_e32 v82, 0x1000, v75
	global_store_dword v82, v2, s[8:9] offset:0 nt
	global_store_dword v82, v6, s[8:9] offset:64 nt
	global_store_dword v82, v10, s[8:9] offset:128 nt
	global_store_dword v82, v14, s[8:9] offset:192 nt
	v_add_u32_e32 v83, 0x1800, v75
	global_store_dword v83, v3, s[8:9] offset:0 nt
	global_store_dword v83, v7, s[8:9] offset:64 nt
	global_store_dword v83, v11, s[8:9] offset:128 nt
	global_store_dword v83, v15, s[8:9] offset:192 nt
	v_add_u32_e32 v80, 0x8000, v75
	global_store_dword v80, v16, s[8:9] offset:0 nt
	global_store_dword v80, v20, s[8:9] offset:64 nt
	global_store_dword v80, v24, s[8:9] offset:128 nt
	global_store_dword v80, v28, s[8:9] offset:192 nt
	v_add_u32_e32 v81, 0x8800, v75
	global_store_dword v81, v17, s[8:9] offset:0 nt
	global_store_dword v81, v21, s[8:9] offset:64 nt
	global_store_dword v81, v25, s[8:9] offset:128 nt
	global_store_dword v81, v29, s[8:9] offset:192 nt
	v_add_u32_e32 v82, 0x9000, v75
	global_store_dword v82, v18, s[8:9] offset:0 nt
	global_store_dword v82, v22, s[8:9] offset:64 nt
	global_store_dword v82, v26, s[8:9] offset:128 nt
	global_store_dword v82, v30, s[8:9] offset:192 nt
	v_add_u32_e32 v83, 0x9800, v75
	global_store_dword v83, v19, s[8:9] offset:0 nt
	global_store_dword v83, v23, s[8:9] offset:64 nt
	global_store_dword v83, v27, s[8:9] offset:128 nt
	global_store_dword v83, v31, s[8:9] offset:192 nt
	v_add_u32_e32 v80, 0x10000, v75
	global_store_dword v80, v32, s[8:9] offset:0 nt
	global_store_dword v80, v36, s[8:9] offset:64 nt
	global_store_dword v80, v40, s[8:9] offset:128 nt
	global_store_dword v80, v44, s[8:9] offset:192 nt
	v_add_u32_e32 v81, 0x10800, v75
	global_store_dword v81, v33, s[8:9] offset:0 nt
	global_store_dword v81, v37, s[8:9] offset:64 nt
	global_store_dword v81, v41, s[8:9] offset:128 nt
	global_store_dword v81, v45, s[8:9] offset:192 nt
	v_add_u32_e32 v82, 0x11000, v75
	global_store_dword v82, v34, s[8:9] offset:0 nt
	global_store_dword v82, v38, s[8:9] offset:64 nt
	global_store_dword v82, v42, s[8:9] offset:128 nt
	global_store_dword v82, v46, s[8:9] offset:192 nt
	v_add_u32_e32 v83, 0x11800, v75
	global_store_dword v83, v35, s[8:9] offset:0 nt
	global_store_dword v83, v39, s[8:9] offset:64 nt
	global_store_dword v83, v43, s[8:9] offset:128 nt
	global_store_dword v83, v47, s[8:9] offset:192 nt
	v_add_u32_e32 v80, 0x18000, v75
	global_store_dword v80, v48, s[8:9] offset:0 nt
	global_store_dword v80, v52, s[8:9] offset:64 nt
	global_store_dword v80, v56, s[8:9] offset:128 nt
	global_store_dword v80, v60, s[8:9] offset:192 nt
	v_add_u32_e32 v81, 0x18800, v75
	global_store_dword v81, v49, s[8:9] offset:0 nt
	global_store_dword v81, v53, s[8:9] offset:64 nt
	global_store_dword v81, v57, s[8:9] offset:128 nt
	global_store_dword v81, v61, s[8:9] offset:192 nt
	v_add_u32_e32 v82, 0x19000, v75
	global_store_dword v82, v50, s[8:9] offset:0 nt
	global_store_dword v82, v54, s[8:9] offset:64 nt
	global_store_dword v82, v58, s[8:9] offset:128 nt
	global_store_dword v82, v62, s[8:9] offset:192 nt
	v_add_u32_e32 v83, 0x19800, v75
	global_store_dword v83, v51, s[8:9] offset:0 nt
	global_store_dword v83, v55, s[8:9] offset:64 nt
	global_store_dword v83, v59, s[8:9] offset:128 nt
	global_store_dword v83, v63, s[8:9] offset:192 nt
.Lie_v_nocache:
	s_movk_i32 s4, 0x3000
	v_mul_lo_u32 v74, v68, s4
	v_lshl_add_u32 v74, v69, 1, v74
	v_mov_b32_e32 v80, v74
	v_bfe_u32 v88, v0, 16, 1
	v_bfe_u32 v89, v1, 16, 1
	v_bfe_u32 v90, v2, 16, 1
	v_bfe_u32 v91, v3, 16, 1
	v_add3_u32 v0, v0, v88, s33
	v_add3_u32 v1, v1, v89, s33
	v_add3_u32 v2, v2, v90, s33
	v_add3_u32 v3, v3, v91, s33
	v_perm_b32 v92, v1, v0, s7
	v_perm_b32 v93, v3, v2, s7
	global_store_dwordx2 v80, v[92:93], s[22:23] offset:0
	v_bfe_u32 v88, v16, 16, 1
	v_bfe_u32 v89, v17, 16, 1
	v_bfe_u32 v90, v18, 16, 1
	v_bfe_u32 v91, v19, 16, 1
	v_add3_u32 v16, v16, v88, s33
	v_add3_u32 v17, v17, v89, s33
	v_add3_u32 v18, v18, v90, s33
	v_add3_u32 v19, v19, v91, s33
	v_perm_b32 v92, v17, v16, s7
	v_perm_b32 v93, v19, v18, s7
	global_store_dwordx2 v80, v[92:93], s[22:23] offset:32
	v_bfe_u32 v88, v32, 16, 1
	v_bfe_u32 v89, v33, 16, 1
	v_bfe_u32 v90, v34, 16, 1
	v_bfe_u32 v91, v35, 16, 1
	v_add3_u32 v32, v32, v88, s33
	v_add3_u32 v33, v33, v89, s33
	v_add3_u32 v34, v34, v90, s33
	v_add3_u32 v35, v35, v91, s33
	v_perm_b32 v92, v33, v32, s7
	v_perm_b32 v93, v35, v34, s7
	global_store_dwordx2 v80, v[92:93], s[22:23] offset:64
	v_bfe_u32 v88, v48, 16, 1
	v_bfe_u32 v89, v49, 16, 1
	v_bfe_u32 v90, v50, 16, 1
	v_bfe_u32 v91, v51, 16, 1
	v_add3_u32 v48, v48, v88, s33
	v_add3_u32 v49, v49, v89, s33
	v_add3_u32 v50, v50, v90, s33
	v_add3_u32 v51, v51, v91, s33
	v_perm_b32 v92, v49, v48, s7
	v_perm_b32 v93, v51, v50, s7
	global_store_dwordx2 v80, v[92:93], s[22:23] offset:96
	v_add_u32_e32 v81, 0x30000, v74
	v_bfe_u32 v88, v4, 16, 1
	v_bfe_u32 v89, v5, 16, 1
	v_bfe_u32 v90, v6, 16, 1
	v_bfe_u32 v91, v7, 16, 1
	v_add3_u32 v4, v4, v88, s33
	v_add3_u32 v5, v5, v89, s33
	v_add3_u32 v6, v6, v90, s33
	v_add3_u32 v7, v7, v91, s33
	v_perm_b32 v92, v5, v4, s7
	v_perm_b32 v93, v7, v6, s7
	global_store_dwordx2 v81, v[92:93], s[22:23] offset:0
	v_bfe_u32 v88, v20, 16, 1
	v_bfe_u32 v89, v21, 16, 1
	v_bfe_u32 v90, v22, 16, 1
	v_bfe_u32 v91, v23, 16, 1
	v_add3_u32 v20, v20, v88, s33
	v_add3_u32 v21, v21, v89, s33
	v_add3_u32 v22, v22, v90, s33
	v_add3_u32 v23, v23, v91, s33
	v_perm_b32 v92, v21, v20, s7
	v_perm_b32 v93, v23, v22, s7
	global_store_dwordx2 v81, v[92:93], s[22:23] offset:32
	v_bfe_u32 v88, v36, 16, 1
	v_bfe_u32 v89, v37, 16, 1
	v_bfe_u32 v90, v38, 16, 1
	v_bfe_u32 v91, v39, 16, 1
	v_add3_u32 v36, v36, v88, s33
	v_add3_u32 v37, v37, v89, s33
	v_add3_u32 v38, v38, v90, s33
	v_add3_u32 v39, v39, v91, s33
	v_perm_b32 v92, v37, v36, s7
	v_perm_b32 v93, v39, v38, s7
	global_store_dwordx2 v81, v[92:93], s[22:23] offset:64
	v_bfe_u32 v88, v52, 16, 1
	v_bfe_u32 v89, v53, 16, 1
	v_bfe_u32 v90, v54, 16, 1
	v_bfe_u32 v91, v55, 16, 1
	v_add3_u32 v52, v52, v88, s33
	v_add3_u32 v53, v53, v89, s33
	v_add3_u32 v54, v54, v90, s33
	v_add3_u32 v55, v55, v91, s33
	v_perm_b32 v92, v53, v52, s7
	v_perm_b32 v93, v55, v54, s7
	global_store_dwordx2 v81, v[92:93], s[22:23] offset:96
	v_add_u32_e32 v82, 0x60000, v74
	v_bfe_u32 v88, v8, 16, 1
	v_bfe_u32 v89, v9, 16, 1
	v_bfe_u32 v90, v10, 16, 1
	v_bfe_u32 v91, v11, 16, 1
	v_add3_u32 v8, v8, v88, s33
	v_add3_u32 v9, v9, v89, s33
	v_add3_u32 v10, v10, v90, s33
	v_add3_u32 v11, v11, v91, s33
	v_perm_b32 v92, v9, v8, s7
	v_perm_b32 v93, v11, v10, s7
	global_store_dwordx2 v82, v[92:93], s[22:23] offset:0
	v_bfe_u32 v88, v24, 16, 1
	v_bfe_u32 v89, v25, 16, 1
	v_bfe_u32 v90, v26, 16, 1
	v_bfe_u32 v91, v27, 16, 1
	v_add3_u32 v24, v24, v88, s33
	v_add3_u32 v25, v25, v89, s33
	v_add3_u32 v26, v26, v90, s33
	v_add3_u32 v27, v27, v91, s33
	v_perm_b32 v92, v25, v24, s7
	v_perm_b32 v93, v27, v26, s7
	global_store_dwordx2 v82, v[92:93], s[22:23] offset:32
	v_bfe_u32 v88, v40, 16, 1
	v_bfe_u32 v89, v41, 16, 1
	v_bfe_u32 v90, v42, 16, 1
	v_bfe_u32 v91, v43, 16, 1
	v_add3_u32 v40, v40, v88, s33
	v_add3_u32 v41, v41, v89, s33
	v_add3_u32 v42, v42, v90, s33
	v_add3_u32 v43, v43, v91, s33
	v_perm_b32 v92, v41, v40, s7
	v_perm_b32 v93, v43, v42, s7
	global_store_dwordx2 v82, v[92:93], s[22:23] offset:64
	v_bfe_u32 v88, v56, 16, 1
	v_bfe_u32 v89, v57, 16, 1
	v_bfe_u32 v90, v58, 16, 1
	v_bfe_u32 v91, v59, 16, 1
	v_add3_u32 v56, v56, v88, s33
	v_add3_u32 v57, v57, v89, s33
	v_add3_u32 v58, v58, v90, s33
	v_add3_u32 v59, v59, v91, s33
	v_perm_b32 v92, v57, v56, s7
	v_perm_b32 v93, v59, v58, s7
	global_store_dwordx2 v82, v[92:93], s[22:23] offset:96
	v_add_u32_e32 v83, 0x90000, v74
	v_bfe_u32 v88, v12, 16, 1
	v_bfe_u32 v89, v13, 16, 1
	v_bfe_u32 v90, v14, 16, 1
	v_bfe_u32 v91, v15, 16, 1
	v_add3_u32 v12, v12, v88, s33
	v_add3_u32 v13, v13, v89, s33
	v_add3_u32 v14, v14, v90, s33
	v_add3_u32 v15, v15, v91, s33
	v_perm_b32 v92, v13, v12, s7
	v_perm_b32 v93, v15, v14, s7
	global_store_dwordx2 v83, v[92:93], s[22:23] offset:0
	v_bfe_u32 v88, v28, 16, 1
	v_bfe_u32 v89, v29, 16, 1
	v_bfe_u32 v90, v30, 16, 1
	v_bfe_u32 v91, v31, 16, 1
	v_add3_u32 v28, v28, v88, s33
	v_add3_u32 v29, v29, v89, s33
	v_add3_u32 v30, v30, v90, s33
	v_add3_u32 v31, v31, v91, s33
	v_perm_b32 v92, v29, v28, s7
	v_perm_b32 v93, v31, v30, s7
	global_store_dwordx2 v83, v[92:93], s[22:23] offset:32
	v_bfe_u32 v88, v44, 16, 1
	v_bfe_u32 v89, v45, 16, 1
	v_bfe_u32 v90, v46, 16, 1
	v_bfe_u32 v91, v47, 16, 1
	v_add3_u32 v44, v44, v88, s33
	v_add3_u32 v45, v45, v89, s33
	v_add3_u32 v46, v46, v90, s33
	v_add3_u32 v47, v47, v91, s33
	v_perm_b32 v92, v45, v44, s7
	v_perm_b32 v93, v47, v46, s7
	global_store_dwordx2 v83, v[92:93], s[22:23] offset:64
	v_bfe_u32 v88, v60, 16, 1
	v_bfe_u32 v89, v61, 16, 1
	v_bfe_u32 v90, v62, 16, 1
	v_bfe_u32 v91, v63, 16, 1
	v_add3_u32 v60, v60, v88, s33
	v_add3_u32 v61, v61, v89, s33
	v_add3_u32 v62, v62, v90, s33
	v_add3_u32 v63, v63, v91, s33
	v_perm_b32 v92, v61, v60, s7
	v_perm_b32 v93, v63, v62, s7
	global_store_dwordx2 v83, v[92:93], s[22:23] offset:96
	s_branch .Lie_done
.Lie_qk:
	s_cmp_eq_u32 s1, 0
	s_cselect_b32 s4, s12, s14
	s_cselect_b32 s5, s13, s15
	s_cselect_b32 s6, 0x3e000000, 1.0
	s_mov_b32 s0, 0x9bf6000
	s_cselect_b32 s0, 0x95f6000, s0
	s_add_u32 s34, s10, s0
	s_addc_u32 s35, s11, 0
	v_lshlrev_b32_e32 v88, 2, v64
	global_load_dword v70, v88, s[4:5] offset:0
	global_load_dword v71, v88, s[4:5] offset:64
	global_load_dword v72, v88, s[4:5] offset:128
	global_load_dword v73, v88, s[4:5] offset:192
	v_lshlrev_b32_e32 v74, 10, v69
	v_lshl_add_u32 v74, v68, 1, v74
	v_lshlrev_b32_e32 v75, 11, v69
	v_lshl_add_u32 v75, v68, 2, v75
	v_mov_b32_e32 v96, 0x3c800000
	s_cmp_eq_u32 s1, 1
	s_cselect_b32 s0, 1, 0
	s_cmpk_lt_u32 s37, 0x1000
	s_cselect_b32 s0, s0, 0
	s_waitcnt vmcnt(0)
	v_mul_f32_e32 v76, v0, v0
	v_mul_f32_e32 v77, v1, v1
	v_mul_f32_e32 v78, v2, v2
	v_mul_f32_e32 v79, v3, v3
	v_fmac_f32_e32 v76, v4, v4
	v_fmac_f32_e32 v77, v5, v5
	v_fmac_f32_e32 v78, v6, v6
	v_fmac_f32_e32 v79, v7, v7
	v_fmac_f32_e32 v76, v8, v8
	v_fmac_f32_e32 v77, v9, v9
	v_fmac_f32_e32 v78, v10, v10
	v_fmac_f32_e32 v79, v11, v11
	v_fmac_f32_e32 v76, v12, v12
	v_fmac_f32_e32 v77, v13, v13
	v_fmac_f32_e32 v78, v14, v14
	v_fmac_f32_e32 v79, v15, v15
	v_add_f32_dpp v76, v76, v76 row_ror:8 row_mask:0xf bank_mask:0xf
	v_add_f32_dpp v77, v77, v77 row_ror:8 row_mask:0xf bank_mask:0xf
	v_add_f32_dpp v78, v78, v78 row_ror:8 row_mask:0xf bank_mask:0xf
	v_add_f32_dpp v79, v79, v79 row_ror:8 row_mask:0xf bank_mask:0xf
	v_add_f32_dpp v76, v76, v76 row_ror:4 row_mask:0xf bank_mask:0xf
	v_add_f32_dpp v77, v77, v77 row_ror:4 row_mask:0xf bank_mask:0xf
	v_add_f32_dpp v78, v78, v78 row_ror:4 row_mask:0xf bank_mask:0xf
	v_add_f32_dpp v79, v79, v79 row_ror:4 row_mask:0xf bank_mask:0xf
	v_add_f32_dpp v76, v76, v76 quad_perm:[2,3,0,1] row_mask:0xf bank_mask:0xf
	v_add_f32_dpp v77, v77, v77 quad_perm:[2,3,0,1] row_mask:0xf bank_mask:0xf
	v_add_f32_dpp v78, v78, v78 quad_perm:[2,3,0,1] row_mask:0xf bank_mask:0xf
	v_add_f32_dpp v79, v79, v79 quad_perm:[2,3,0,1] row_mask:0xf bank_mask:0xf
	v_add_f32_dpp v76, v76, v76 quad_perm:[1,0,3,2] row_mask:0xf bank_mask:0xf
	v_add_f32_dpp v77, v77, v77 quad_perm:[1,0,3,2] row_mask:0xf bank_mask:0xf
	v_add_f32_dpp v78, v78, v78 quad_perm:[1,0,3,2] row_mask:0xf bank_mask:0xf
	v_add_f32_dpp v79, v79, v79 quad_perm:[1,0,3,2] row_mask:0xf bank_mask:0xf
	v_fmaak_f32 v76, v96, v76, 0x358637bd
	v_fmaak_f32 v77, v96, v77, 0x358637bd
	v_fmaak_f32 v78, v96, v78, 0x358637bd
	v_fmaak_f32 v79, v96, v79, 0x358637bd
	v_rsq_f32_e32 v76, v76
	v_rsq_f32_e32 v77, v77
	v_rsq_f32_e32 v78, v78
	v_rsq_f32_e32 v79, v79
	v_mov_b32_e32 v80, v74
	v_add_u32_e32 v81, 0x400, v74
	v_add_u32_e32 v82, 0x800, v74
	v_add_u32_e32 v83, 0xc00, v74
	v_mul_f32_e32 v76, s6, v76
	v_mul_f32_e32 v77, s6, v77
	v_mul_f32_e32 v78, s6, v78
	v_mul_f32_e32 v79, s6, v79
	v_mul_f32_e32 v0, v0, v76
	v_mul_f32_e32 v4, v4, v76
	v_mul_f32_e32 v8, v8, v76
	v_mul_f32_e32 v12, v12, v76
	v_mul_f32_e32 v1, v1, v77
	v_mul_f32_e32 v5, v5, v77
	v_mul_f32_e32 v9, v9, v77
	v_mul_f32_e32 v13, v13, v77
	v_mul_f32_e32 v2, v2, v78
	v_mul_f32_e32 v6, v6, v78
	v_mul_f32_e32 v10, v10, v78
	v_mul_f32_e32 v14, v14, v78
	v_mul_f32_e32 v3, v3, v79
	v_mul_f32_e32 v7, v7, v79
	v_mul_f32_e32 v11, v11, v79
	v_mul_f32_e32 v15, v15, v79
	v_mul_f32_e32 v0, v0, v70
	v_mul_f32_e32 v4, v4, v71
	v_mul_f32_e32 v8, v8, v72
	v_mul_f32_e32 v12, v12, v73
	v_mul_f32_e32 v1, v1, v70
	v_mul_f32_e32 v5, v5, v71
	v_mul_f32_e32 v9, v9, v72
	v_mul_f32_e32 v13, v13, v73
	v_mul_f32_e32 v2, v2, v70
	v_mul_f32_e32 v6, v6, v71
	v_mul_f32_e32 v10, v10, v72
	v_mul_f32_e32 v14, v14, v73
	v_mul_f32_e32 v3, v3, v70
	v_mul_f32_e32 v7, v7, v71
	v_mul_f32_e32 v11, v11, v72
	v_mul_f32_e32 v15, v15, v73
	s_cmp_eq_u32 s0, 0
	s_cbranch_scc1 .Lie_nokc_0
	v_mov_b32_e32 v84, v75
	v_add_u32_e32 v85, 0x800, v75
	v_add_u32_e32 v86, 0x1000, v75
	v_add_u32_e32 v87, 0x1800, v75
	global_store_dword v84, v0, s[28:29] offset:0 nt
	global_store_dword v84, v4, s[28:29] offset:64 nt
	global_store_dword v84, v8, s[28:29] offset:128 nt
	global_store_dword v84, v12, s[28:29] offset:192 nt
	global_store_dword v85, v1, s[28:29] offset:0 nt
	global_store_dword v85, v5, s[28:29] offset:64 nt
	global_store_dword v85, v9, s[28:29] offset:128 nt
	global_store_dword v85, v13, s[28:29] offset:192 nt
	global_store_dword v86, v2, s[28:29] offset:0 nt
	global_store_dword v86, v6, s[28:29] offset:64 nt
	global_store_dword v86, v10, s[28:29] offset:128 nt
	global_store_dword v86, v14, s[28:29] offset:192 nt
	global_store_dword v87, v3, s[28:29] offset:0 nt
	global_store_dword v87, v7, s[28:29] offset:64 nt
	global_store_dword v87, v11, s[28:29] offset:128 nt
	global_store_dword v87, v15, s[28:29] offset:192 nt
.Lie_nokc_0:
	v_bfe_u32 v88, v0, 16, 1
	v_bfe_u32 v89, v4, 16, 1
	v_bfe_u32 v90, v8, 16, 1
	v_bfe_u32 v91, v12, 16, 1
	v_add3_u32 v0, v0, v88, s33
	v_add3_u32 v4, v4, v89, s33
	v_add3_u32 v8, v8, v90, s33
	v_add3_u32 v12, v12, v91, s33
	v_bfe_u32 v88, v1, 16, 1
	v_bfe_u32 v89, v5, 16, 1
	v_bfe_u32 v90, v9, 16, 1
	v_bfe_u32 v91, v13, 16, 1
	v_add3_u32 v1, v1, v88, s33
	v_add3_u32 v5, v5, v89, s33
	v_add3_u32 v9, v9, v90, s33
	v_add3_u32 v13, v13, v91, s33
	v_bfe_u32 v88, v2, 16, 1
	v_bfe_u32 v89, v6, 16, 1
	v_bfe_u32 v90, v10, 16, 1
	v_bfe_u32 v91, v14, 16, 1
	v_add3_u32 v2, v2, v88, s33
	v_add3_u32 v6, v6, v89, s33
	v_add3_u32 v10, v10, v90, s33
	v_add3_u32 v14, v14, v91, s33
	v_bfe_u32 v88, v3, 16, 1
	v_bfe_u32 v89, v7, 16, 1
	v_bfe_u32 v90, v11, 16, 1
	v_bfe_u32 v91, v15, 16, 1
	v_add3_u32 v3, v3, v88, s33
	v_add3_u32 v7, v7, v89, s33
	v_add3_u32 v11, v11, v90, s33
	v_add3_u32 v15, v15, v91, s33
	s_cmp_eq_u32 s1, 0
	s_cbranch_scc0 .Lie_kst_0
	global_store_short_d16_hi v80, v0, s[34:35] offset:0 nt
	global_store_short_d16_hi v80, v4, s[34:35] offset:32 nt
	global_store_short_d16_hi v80, v8, s[34:35] offset:64 nt
	global_store_short_d16_hi v80, v12, s[34:35] offset:96 nt
	global_store_short_d16_hi v81, v1, s[34:35] offset:0 nt
	global_store_short_d16_hi v81, v5, s[34:35] offset:32 nt
	global_store_short_d16_hi v81, v9, s[34:35] offset:64 nt
	global_store_short_d16_hi v81, v13, s[34:35] offset:96 nt
	global_store_short_d16_hi v82, v2, s[34:35] offset:0 nt
	global_store_short_d16_hi v82, v6, s[34:35] offset:32 nt
	global_store_short_d16_hi v82, v10, s[34:35] offset:64 nt
	global_store_short_d16_hi v82, v14, s[34:35] offset:96 nt
	global_store_short_d16_hi v83, v3, s[34:35] offset:0 nt
	global_store_short_d16_hi v83, v7, s[34:35] offset:32 nt
	global_store_short_d16_hi v83, v11, s[34:35] offset:64 nt
	global_store_short_d16_hi v83, v15, s[34:35] offset:96 nt
	s_branch .Lie_qkn_0
.Lie_kst_0:
	global_store_short_d16_hi v80, v0, s[34:35] offset:0
	global_store_short_d16_hi v80, v4, s[34:35] offset:32
	global_store_short_d16_hi v80, v8, s[34:35] offset:64
	global_store_short_d16_hi v80, v12, s[34:35] offset:96
	global_store_short_d16_hi v81, v1, s[34:35] offset:0
	global_store_short_d16_hi v81, v5, s[34:35] offset:32
	global_store_short_d16_hi v81, v9, s[34:35] offset:64
	global_store_short_d16_hi v81, v13, s[34:35] offset:96
	global_store_short_d16_hi v82, v2, s[34:35] offset:0
	global_store_short_d16_hi v82, v6, s[34:35] offset:32
	global_store_short_d16_hi v82, v10, s[34:35] offset:64
	global_store_short_d16_hi v82, v14, s[34:35] offset:96
	global_store_short_d16_hi v83, v3, s[34:35] offset:0
	global_store_short_d16_hi v83, v7, s[34:35] offset:32
	global_store_short_d16_hi v83, v11, s[34:35] offset:64
	global_store_short_d16_hi v83, v15, s[34:35] offset:96
.Lie_qkn_0:
	v_mul_f32_e32 v76, v16, v16
	v_mul_f32_e32 v77, v17, v17
	v_mul_f32_e32 v78, v18, v18
	v_mul_f32_e32 v79, v19, v19
	v_fmac_f32_e32 v76, v20, v20
	v_fmac_f32_e32 v77, v21, v21
	v_fmac_f32_e32 v78, v22, v22
	v_fmac_f32_e32 v79, v23, v23
	v_fmac_f32_e32 v76, v24, v24
	v_fmac_f32_e32 v77, v25, v25
	v_fmac_f32_e32 v78, v26, v26
	v_fmac_f32_e32 v79, v27, v27
	v_fmac_f32_e32 v76, v28, v28
	v_fmac_f32_e32 v77, v29, v29
	v_fmac_f32_e32 v78, v30, v30
	v_fmac_f32_e32 v79, v31, v31
	v_add_f32_dpp v76, v76, v76 row_ror:8 row_mask:0xf bank_mask:0xf
	v_add_f32_dpp v77, v77, v77 row_ror:8 row_mask:0xf bank_mask:0xf
	v_add_f32_dpp v78, v78, v78 row_ror:8 row_mask:0xf bank_mask:0xf
	v_add_f32_dpp v79, v79, v79 row_ror:8 row_mask:0xf bank_mask:0xf
	v_add_f32_dpp v76, v76, v76 row_ror:4 row_mask:0xf bank_mask:0xf
	v_add_f32_dpp v77, v77, v77 row_ror:4 row_mask:0xf bank_mask:0xf
	v_add_f32_dpp v78, v78, v78 row_ror:4 row_mask:0xf bank_mask:0xf
	v_add_f32_dpp v79, v79, v79 row_ror:4 row_mask:0xf bank_mask:0xf
	v_add_f32_dpp v76, v76, v76 quad_perm:[2,3,0,1] row_mask:0xf bank_mask:0xf
	v_add_f32_dpp v77, v77, v77 quad_perm:[2,3,0,1] row_mask:0xf bank_mask:0xf
	v_add_f32_dpp v78, v78, v78 quad_perm:[2,3,0,1] row_mask:0xf bank_mask:0xf
	v_add_f32_dpp v79, v79, v79 quad_perm:[2,3,0,1] row_mask:0xf bank_mask:0xf
	v_add_f32_dpp v76, v76, v76 quad_perm:[1,0,3,2] row_mask:0xf bank_mask:0xf
	v_add_f32_dpp v77, v77, v77 quad_perm:[1,0,3,2] row_mask:0xf bank_mask:0xf
	v_add_f32_dpp v78, v78, v78 quad_perm:[1,0,3,2] row_mask:0xf bank_mask:0xf
	v_add_f32_dpp v79, v79, v79 quad_perm:[1,0,3,2] row_mask:0xf bank_mask:0xf
	v_fmaak_f32 v76, v96, v76, 0x358637bd
	v_fmaak_f32 v77, v96, v77, 0x358637bd
	v_fmaak_f32 v78, v96, v78, 0x358637bd
	v_fmaak_f32 v79, v96, v79, 0x358637bd
	v_rsq_f32_e32 v76, v76
	v_rsq_f32_e32 v77, v77
	v_rsq_f32_e32 v78, v78
	v_rsq_f32_e32 v79, v79
	v_add_u32_e32 v80, 0x4000, v74
	v_add_u32_e32 v81, 0x4400, v74
	v_add_u32_e32 v82, 0x4800, v74
	v_add_u32_e32 v83, 0x4c00, v74
	v_mul_f32_e32 v76, s6, v76
	v_mul_f32_e32 v77, s6, v77
	v_mul_f32_e32 v78, s6, v78
	v_mul_f32_e32 v79, s6, v79
	v_mul_f32_e32 v16, v16, v76
	v_mul_f32_e32 v20, v20, v76
	v_mul_f32_e32 v24, v24, v76
	v_mul_f32_e32 v28, v28, v76
	v_mul_f32_e32 v17, v17, v77
	v_mul_f32_e32 v21, v21, v77
	v_mul_f32_e32 v25, v25, v77
	v_mul_f32_e32 v29, v29, v77
	v_mul_f32_e32 v18, v18, v78
	v_mul_f32_e32 v22, v22, v78
	v_mul_f32_e32 v26, v26, v78
	v_mul_f32_e32 v30, v30, v78
	v_mul_f32_e32 v19, v19, v79
	v_mul_f32_e32 v23, v23, v79
	v_mul_f32_e32 v27, v27, v79
	v_mul_f32_e32 v31, v31, v79
	v_mul_f32_e32 v16, v16, v70
	v_mul_f32_e32 v20, v20, v71
	v_mul_f32_e32 v24, v24, v72
	v_mul_f32_e32 v28, v28, v73
	v_mul_f32_e32 v17, v17, v70
	v_mul_f32_e32 v21, v21, v71
	v_mul_f32_e32 v25, v25, v72
	v_mul_f32_e32 v29, v29, v73
	v_mul_f32_e32 v18, v18, v70
	v_mul_f32_e32 v22, v22, v71
	v_mul_f32_e32 v26, v26, v72
	v_mul_f32_e32 v30, v30, v73
	v_mul_f32_e32 v19, v19, v70
	v_mul_f32_e32 v23, v23, v71
	v_mul_f32_e32 v27, v27, v72
	v_mul_f32_e32 v31, v31, v73
	s_cmp_eq_u32 s0, 0
	s_cbranch_scc1 .Lie_nokc_1
	v_add_u32_e32 v84, 0x8000, v75
	v_add_u32_e32 v85, 0x8800, v75
	v_add_u32_e32 v86, 0x9000, v75
	v_add_u32_e32 v87, 0x9800, v75
	global_store_dword v84, v16, s[28:29] offset:0 nt
	global_store_dword v84, v20, s[28:29] offset:64 nt
	global_store_dword v84, v24, s[28:29] offset:128 nt
	global_store_dword v84, v28, s[28:29] offset:192 nt
	global_store_dword v85, v17, s[28:29] offset:0 nt
	global_store_dword v85, v21, s[28:29] offset:64 nt
	global_store_dword v85, v25, s[28:29] offset:128 nt
	global_store_dword v85, v29, s[28:29] offset:192 nt
	global_store_dword v86, v18, s[28:29] offset:0 nt
	global_store_dword v86, v22, s[28:29] offset:64 nt
	global_store_dword v86, v26, s[28:29] offset:128 nt
	global_store_dword v86, v30, s[28:29] offset:192 nt
	global_store_dword v87, v19, s[28:29] offset:0 nt
	global_store_dword v87, v23, s[28:29] offset:64 nt
	global_store_dword v87, v27, s[28:29] offset:128 nt
	global_store_dword v87, v31, s[28:29] offset:192 nt
.Lie_nokc_1:
	v_bfe_u32 v88, v16, 16, 1
	v_bfe_u32 v89, v20, 16, 1
	v_bfe_u32 v90, v24, 16, 1
	v_bfe_u32 v91, v28, 16, 1
	v_add3_u32 v16, v16, v88, s33
	v_add3_u32 v20, v20, v89, s33
	v_add3_u32 v24, v24, v90, s33
	v_add3_u32 v28, v28, v91, s33
	v_bfe_u32 v88, v17, 16, 1
	v_bfe_u32 v89, v21, 16, 1
	v_bfe_u32 v90, v25, 16, 1
	v_bfe_u32 v91, v29, 16, 1
	v_add3_u32 v17, v17, v88, s33
	v_add3_u32 v21, v21, v89, s33
	v_add3_u32 v25, v25, v90, s33
	v_add3_u32 v29, v29, v91, s33
	v_bfe_u32 v88, v18, 16, 1
	v_bfe_u32 v89, v22, 16, 1
	v_bfe_u32 v90, v26, 16, 1
	v_bfe_u32 v91, v30, 16, 1
	v_add3_u32 v18, v18, v88, s33
	v_add3_u32 v22, v22, v89, s33
	v_add3_u32 v26, v26, v90, s33
	v_add3_u32 v30, v30, v91, s33
	v_bfe_u32 v88, v19, 16, 1
	v_bfe_u32 v89, v23, 16, 1
	v_bfe_u32 v90, v27, 16, 1
	v_bfe_u32 v91, v31, 16, 1
	v_add3_u32 v19, v19, v88, s33
	v_add3_u32 v23, v23, v89, s33
	v_add3_u32 v27, v27, v90, s33
	v_add3_u32 v31, v31, v91, s33
	s_cmp_eq_u32 s1, 0
	s_cbranch_scc0 .Lie_kst_1
	global_store_short_d16_hi v80, v16, s[34:35] offset:0 nt
	global_store_short_d16_hi v80, v20, s[34:35] offset:32 nt
	global_store_short_d16_hi v80, v24, s[34:35] offset:64 nt
	global_store_short_d16_hi v80, v28, s[34:35] offset:96 nt
	global_store_short_d16_hi v81, v17, s[34:35] offset:0 nt
	global_store_short_d16_hi v81, v21, s[34:35] offset:32 nt
	global_store_short_d16_hi v81, v25, s[34:35] offset:64 nt
	global_store_short_d16_hi v81, v29, s[34:35] offset:96 nt
	global_store_short_d16_hi v82, v18, s[34:35] offset:0 nt
	global_store_short_d16_hi v82, v22, s[34:35] offset:32 nt
	global_store_short_d16_hi v82, v26, s[34:35] offset:64 nt
	global_store_short_d16_hi v82, v30, s[34:35] offset:96 nt
	global_store_short_d16_hi v83, v19, s[34:35] offset:0 nt
	global_store_short_d16_hi v83, v23, s[34:35] offset:32 nt
	global_store_short_d16_hi v83, v27, s[34:35] offset:64 nt
	global_store_short_d16_hi v83, v31, s[34:35] offset:96 nt
	s_branch .Lie_qkn_1
.Lie_kst_1:
	global_store_short_d16_hi v80, v16, s[34:35] offset:0
	global_store_short_d16_hi v80, v20, s[34:35] offset:32
	global_store_short_d16_hi v80, v24, s[34:35] offset:64
	global_store_short_d16_hi v80, v28, s[34:35] offset:96
	global_store_short_d16_hi v81, v17, s[34:35] offset:0
	global_store_short_d16_hi v81, v21, s[34:35] offset:32
	global_store_short_d16_hi v81, v25, s[34:35] offset:64
	global_store_short_d16_hi v81, v29, s[34:35] offset:96
	global_store_short_d16_hi v82, v18, s[34:35] offset:0
	global_store_short_d16_hi v82, v22, s[34:35] offset:32
	global_store_short_d16_hi v82, v26, s[34:35] offset:64
	global_store_short_d16_hi v82, v30, s[34:35] offset:96
	global_store_short_d16_hi v83, v19, s[34:35] offset:0
	global_store_short_d16_hi v83, v23, s[34:35] offset:32
	global_store_short_d16_hi v83, v27, s[34:35] offset:64
	global_store_short_d16_hi v83, v31, s[34:35] offset:96
.Lie_qkn_1:
	v_mul_f32_e32 v76, v32, v32
	v_mul_f32_e32 v77, v33, v33
	v_mul_f32_e32 v78, v34, v34
	v_mul_f32_e32 v79, v35, v35
	v_fmac_f32_e32 v76, v36, v36
	v_fmac_f32_e32 v77, v37, v37
	v_fmac_f32_e32 v78, v38, v38
	v_fmac_f32_e32 v79, v39, v39
	v_fmac_f32_e32 v76, v40, v40
	v_fmac_f32_e32 v77, v41, v41
	v_fmac_f32_e32 v78, v42, v42
	v_fmac_f32_e32 v79, v43, v43
	v_fmac_f32_e32 v76, v44, v44
	v_fmac_f32_e32 v77, v45, v45
	v_fmac_f32_e32 v78, v46, v46
	v_fmac_f32_e32 v79, v47, v47
	v_add_f32_dpp v76, v76, v76 row_ror:8 row_mask:0xf bank_mask:0xf
	v_add_f32_dpp v77, v77, v77 row_ror:8 row_mask:0xf bank_mask:0xf
	v_add_f32_dpp v78, v78, v78 row_ror:8 row_mask:0xf bank_mask:0xf
	v_add_f32_dpp v79, v79, v79 row_ror:8 row_mask:0xf bank_mask:0xf
	v_add_f32_dpp v76, v76, v76 row_ror:4 row_mask:0xf bank_mask:0xf
	v_add_f32_dpp v77, v77, v77 row_ror:4 row_mask:0xf bank_mask:0xf
	v_add_f32_dpp v78, v78, v78 row_ror:4 row_mask:0xf bank_mask:0xf
	v_add_f32_dpp v79, v79, v79 row_ror:4 row_mask:0xf bank_mask:0xf
	v_add_f32_dpp v76, v76, v76 quad_perm:[2,3,0,1] row_mask:0xf bank_mask:0xf
	v_add_f32_dpp v77, v77, v77 quad_perm:[2,3,0,1] row_mask:0xf bank_mask:0xf
	v_add_f32_dpp v78, v78, v78 quad_perm:[2,3,0,1] row_mask:0xf bank_mask:0xf
	v_add_f32_dpp v79, v79, v79 quad_perm:[2,3,0,1] row_mask:0xf bank_mask:0xf
	v_add_f32_dpp v76, v76, v76 quad_perm:[1,0,3,2] row_mask:0xf bank_mask:0xf
	v_add_f32_dpp v77, v77, v77 quad_perm:[1,0,3,2] row_mask:0xf bank_mask:0xf
	v_add_f32_dpp v78, v78, v78 quad_perm:[1,0,3,2] row_mask:0xf bank_mask:0xf
	v_add_f32_dpp v79, v79, v79 quad_perm:[1,0,3,2] row_mask:0xf bank_mask:0xf
	v_fmaak_f32 v76, v96, v76, 0x358637bd
	v_fmaak_f32 v77, v96, v77, 0x358637bd
	v_fmaak_f32 v78, v96, v78, 0x358637bd
	v_fmaak_f32 v79, v96, v79, 0x358637bd
	v_rsq_f32_e32 v76, v76
	v_rsq_f32_e32 v77, v77
	v_rsq_f32_e32 v78, v78
	v_rsq_f32_e32 v79, v79
	v_add_u32_e32 v80, 0x8000, v74
	v_add_u32_e32 v81, 0x8400, v74
	v_add_u32_e32 v82, 0x8800, v74
	v_add_u32_e32 v83, 0x8c00, v74
	v_mul_f32_e32 v76, s6, v76
	v_mul_f32_e32 v77, s6, v77
	v_mul_f32_e32 v78, s6, v78
	v_mul_f32_e32 v79, s6, v79
	v_mul_f32_e32 v32, v32, v76
	v_mul_f32_e32 v36, v36, v76
	v_mul_f32_e32 v40, v40, v76
	v_mul_f32_e32 v44, v44, v76
	v_mul_f32_e32 v33, v33, v77
	v_mul_f32_e32 v37, v37, v77
	v_mul_f32_e32 v41, v41, v77
	v_mul_f32_e32 v45, v45, v77
	v_mul_f32_e32 v34, v34, v78
	v_mul_f32_e32 v38, v38, v78
	v_mul_f32_e32 v42, v42, v78
	v_mul_f32_e32 v46, v46, v78
	v_mul_f32_e32 v35, v35, v79
	v_mul_f32_e32 v39, v39, v79
	v_mul_f32_e32 v43, v43, v79
	v_mul_f32_e32 v47, v47, v79
	v_mul_f32_e32 v32, v32, v70
	v_mul_f32_e32 v36, v36, v71
	v_mul_f32_e32 v40, v40, v72
	v_mul_f32_e32 v44, v44, v73
	v_mul_f32_e32 v33, v33, v70
	v_mul_f32_e32 v37, v37, v71
	v_mul_f32_e32 v41, v41, v72
	v_mul_f32_e32 v45, v45, v73
	v_mul_f32_e32 v34, v34, v70
	v_mul_f32_e32 v38, v38, v71
	v_mul_f32_e32 v42, v42, v72
	v_mul_f32_e32 v46, v46, v73
	v_mul_f32_e32 v35, v35, v70
	v_mul_f32_e32 v39, v39, v71
	v_mul_f32_e32 v43, v43, v72
	v_mul_f32_e32 v47, v47, v73
	s_cmp_eq_u32 s0, 0
	s_cbranch_scc1 .Lie_nokc_2
	v_add_u32_e32 v84, 0x10000, v75
	v_add_u32_e32 v85, 0x10800, v75
	v_add_u32_e32 v86, 0x11000, v75
	v_add_u32_e32 v87, 0x11800, v75
	global_store_dword v84, v32, s[28:29] offset:0 nt
	global_store_dword v84, v36, s[28:29] offset:64 nt
	global_store_dword v84, v40, s[28:29] offset:128 nt
	global_store_dword v84, v44, s[28:29] offset:192 nt
	global_store_dword v85, v33, s[28:29] offset:0 nt
	global_store_dword v85, v37, s[28:29] offset:64 nt
	global_store_dword v85, v41, s[28:29] offset:128 nt
	global_store_dword v85, v45, s[28:29] offset:192 nt
	global_store_dword v86, v34, s[28:29] offset:0 nt
	global_store_dword v86, v38, s[28:29] offset:64 nt
	global_store_dword v86, v42, s[28:29] offset:128 nt
	global_store_dword v86, v46, s[28:29] offset:192 nt
	global_store_dword v87, v35, s[28:29] offset:0 nt
	global_store_dword v87, v39, s[28:29] offset:64 nt
	global_store_dword v87, v43, s[28:29] offset:128 nt
	global_store_dword v87, v47, s[28:29] offset:192 nt
.Lie_nokc_2:
	v_bfe_u32 v88, v32, 16, 1
	v_bfe_u32 v89, v36, 16, 1
	v_bfe_u32 v90, v40, 16, 1
	v_bfe_u32 v91, v44, 16, 1
	v_add3_u32 v32, v32, v88, s33
	v_add3_u32 v36, v36, v89, s33
	v_add3_u32 v40, v40, v90, s33
	v_add3_u32 v44, v44, v91, s33
	v_bfe_u32 v88, v33, 16, 1
	v_bfe_u32 v89, v37, 16, 1
	v_bfe_u32 v90, v41, 16, 1
	v_bfe_u32 v91, v45, 16, 1
	v_add3_u32 v33, v33, v88, s33
	v_add3_u32 v37, v37, v89, s33
	v_add3_u32 v41, v41, v90, s33
	v_add3_u32 v45, v45, v91, s33
	v_bfe_u32 v88, v34, 16, 1
	v_bfe_u32 v89, v38, 16, 1
	v_bfe_u32 v90, v42, 16, 1
	v_bfe_u32 v91, v46, 16, 1
	v_add3_u32 v34, v34, v88, s33
	v_add3_u32 v38, v38, v89, s33
	v_add3_u32 v42, v42, v90, s33
	v_add3_u32 v46, v46, v91, s33
	v_bfe_u32 v88, v35, 16, 1
	v_bfe_u32 v89, v39, 16, 1
	v_bfe_u32 v90, v43, 16, 1
	v_bfe_u32 v91, v47, 16, 1
	v_add3_u32 v35, v35, v88, s33
	v_add3_u32 v39, v39, v89, s33
	v_add3_u32 v43, v43, v90, s33
	v_add3_u32 v47, v47, v91, s33
	s_cmp_eq_u32 s1, 0
	s_cbranch_scc0 .Lie_kst_2
	global_store_short_d16_hi v80, v32, s[34:35] offset:0 nt
	global_store_short_d16_hi v80, v36, s[34:35] offset:32 nt
	global_store_short_d16_hi v80, v40, s[34:35] offset:64 nt
	global_store_short_d16_hi v80, v44, s[34:35] offset:96 nt
	global_store_short_d16_hi v81, v33, s[34:35] offset:0 nt
	global_store_short_d16_hi v81, v37, s[34:35] offset:32 nt
	global_store_short_d16_hi v81, v41, s[34:35] offset:64 nt
	global_store_short_d16_hi v81, v45, s[34:35] offset:96 nt
	global_store_short_d16_hi v82, v34, s[34:35] offset:0 nt
	global_store_short_d16_hi v82, v38, s[34:35] offset:32 nt
	global_store_short_d16_hi v82, v42, s[34:35] offset:64 nt
	global_store_short_d16_hi v82, v46, s[34:35] offset:96 nt
	global_store_short_d16_hi v83, v35, s[34:35] offset:0 nt
	global_store_short_d16_hi v83, v39, s[34:35] offset:32 nt
	global_store_short_d16_hi v83, v43, s[34:35] offset:64 nt
	global_store_short_d16_hi v83, v47, s[34:35] offset:96 nt
	s_branch .Lie_qkn_2
.Lie_kst_2:
	global_store_short_d16_hi v80, v32, s[34:35] offset:0
	global_store_short_d16_hi v80, v36, s[34:35] offset:32
	global_store_short_d16_hi v80, v40, s[34:35] offset:64
	global_store_short_d16_hi v80, v44, s[34:35] offset:96
	global_store_short_d16_hi v81, v33, s[34:35] offset:0
	global_store_short_d16_hi v81, v37, s[34:35] offset:32
	global_store_short_d16_hi v81, v41, s[34:35] offset:64
	global_store_short_d16_hi v81, v45, s[34:35] offset:96
	global_store_short_d16_hi v82, v34, s[34:35] offset:0
	global_store_short_d16_hi v82, v38, s[34:35] offset:32
	global_store_short_d16_hi v82, v42, s[34:35] offset:64
	global_store_short_d16_hi v82, v46, s[34:35] offset:96
	global_store_short_d16_hi v83, v35, s[34:35] offset:0
	global_store_short_d16_hi v83, v39, s[34:35] offset:32
	global_store_short_d16_hi v83, v43, s[34:35] offset:64
	global_store_short_d16_hi v83, v47, s[34:35] offset:96
.Lie_qkn_2:
	v_mul_f32_e32 v76, v48, v48
	v_mul_f32_e32 v77, v49, v49
	v_mul_f32_e32 v78, v50, v50
	v_mul_f32_e32 v79, v51, v51
	v_fmac_f32_e32 v76, v52, v52
	v_fmac_f32_e32 v77, v53, v53
	v_fmac_f32_e32 v78, v54, v54
	v_fmac_f32_e32 v79, v55, v55
	v_fmac_f32_e32 v76, v56, v56
	v_fmac_f32_e32 v77, v57, v57
	v_fmac_f32_e32 v78, v58, v58
	v_fmac_f32_e32 v79, v59, v59
	v_fmac_f32_e32 v76, v60, v60
	v_fmac_f32_e32 v77, v61, v61
	v_fmac_f32_e32 v78, v62, v62
	v_fmac_f32_e32 v79, v63, v63
	v_add_f32_dpp v76, v76, v76 row_ror:8 row_mask:0xf bank_mask:0xf
	v_add_f32_dpp v77, v77, v77 row_ror:8 row_mask:0xf bank_mask:0xf
	v_add_f32_dpp v78, v78, v78 row_ror:8 row_mask:0xf bank_mask:0xf
	v_add_f32_dpp v79, v79, v79 row_ror:8 row_mask:0xf bank_mask:0xf
	v_add_f32_dpp v76, v76, v76 row_ror:4 row_mask:0xf bank_mask:0xf
	v_add_f32_dpp v77, v77, v77 row_ror:4 row_mask:0xf bank_mask:0xf
	v_add_f32_dpp v78, v78, v78 row_ror:4 row_mask:0xf bank_mask:0xf
	v_add_f32_dpp v79, v79, v79 row_ror:4 row_mask:0xf bank_mask:0xf
	v_add_f32_dpp v76, v76, v76 quad_perm:[2,3,0,1] row_mask:0xf bank_mask:0xf
	v_add_f32_dpp v77, v77, v77 quad_perm:[2,3,0,1] row_mask:0xf bank_mask:0xf
	v_add_f32_dpp v78, v78, v78 quad_perm:[2,3,0,1] row_mask:0xf bank_mask:0xf
	v_add_f32_dpp v79, v79, v79 quad_perm:[2,3,0,1] row_mask:0xf bank_mask:0xf
	v_add_f32_dpp v76, v76, v76 quad_perm:[1,0,3,2] row_mask:0xf bank_mask:0xf
	v_add_f32_dpp v77, v77, v77 quad_perm:[1,0,3,2] row_mask:0xf bank_mask:0xf
	v_add_f32_dpp v78, v78, v78 quad_perm:[1,0,3,2] row_mask:0xf bank_mask:0xf
	v_add_f32_dpp v79, v79, v79 quad_perm:[1,0,3,2] row_mask:0xf bank_mask:0xf
	v_fmaak_f32 v76, v96, v76, 0x358637bd
	v_fmaak_f32 v77, v96, v77, 0x358637bd
	v_fmaak_f32 v78, v96, v78, 0x358637bd
	v_fmaak_f32 v79, v96, v79, 0x358637bd
	v_rsq_f32_e32 v76, v76
	v_rsq_f32_e32 v77, v77
	v_rsq_f32_e32 v78, v78
	v_rsq_f32_e32 v79, v79
	v_add_u32_e32 v80, 0xc000, v74
	v_add_u32_e32 v81, 0xc400, v74
	v_add_u32_e32 v82, 0xc800, v74
	v_add_u32_e32 v83, 0xcc00, v74
	v_mul_f32_e32 v76, s6, v76
	v_mul_f32_e32 v77, s6, v77
	v_mul_f32_e32 v78, s6, v78
	v_mul_f32_e32 v79, s6, v79
	v_mul_f32_e32 v48, v48, v76
	v_mul_f32_e32 v52, v52, v76
	v_mul_f32_e32 v56, v56, v76
	v_mul_f32_e32 v60, v60, v76
	v_mul_f32_e32 v49, v49, v77
	v_mul_f32_e32 v53, v53, v77
	v_mul_f32_e32 v57, v57, v77
	v_mul_f32_e32 v61, v61, v77
	v_mul_f32_e32 v50, v50, v78
	v_mul_f32_e32 v54, v54, v78
	v_mul_f32_e32 v58, v58, v78
	v_mul_f32_e32 v62, v62, v78
	v_mul_f32_e32 v51, v51, v79
	v_mul_f32_e32 v55, v55, v79
	v_mul_f32_e32 v59, v59, v79
	v_mul_f32_e32 v63, v63, v79
	v_mul_f32_e32 v48, v48, v70
	v_mul_f32_e32 v52, v52, v71
	v_mul_f32_e32 v56, v56, v72
	v_mul_f32_e32 v60, v60, v73
	v_mul_f32_e32 v49, v49, v70
	v_mul_f32_e32 v53, v53, v71
	v_mul_f32_e32 v57, v57, v72
	v_mul_f32_e32 v61, v61, v73
	v_mul_f32_e32 v50, v50, v70
	v_mul_f32_e32 v54, v54, v71
	v_mul_f32_e32 v58, v58, v72
	v_mul_f32_e32 v62, v62, v73
	v_mul_f32_e32 v51, v51, v70
	v_mul_f32_e32 v55, v55, v71
	v_mul_f32_e32 v59, v59, v72
	v_mul_f32_e32 v63, v63, v73
	s_cmp_eq_u32 s0, 0
	s_cbranch_scc1 .Lie_nokc_3
	v_add_u32_e32 v84, 0x18000, v75
	v_add_u32_e32 v85, 0x18800, v75
	v_add_u32_e32 v86, 0x19000, v75
	v_add_u32_e32 v87, 0x19800, v75
	global_store_dword v84, v48, s[28:29] offset:0 nt
	global_store_dword v84, v52, s[28:29] offset:64 nt
	global_store_dword v84, v56, s[28:29] offset:128 nt
	global_store_dword v84, v60, s[28:29] offset:192 nt
	global_store_dword v85, v49, s[28:29] offset:0 nt
	global_store_dword v85, v53, s[28:29] offset:64 nt
	global_store_dword v85, v57, s[28:29] offset:128 nt
	global_store_dword v85, v61, s[28:29] offset:192 nt
	global_store_dword v86, v50, s[28:29] offset:0 nt
	global_store_dword v86, v54, s[28:29] offset:64 nt
	global_store_dword v86, v58, s[28:29] offset:128 nt
	global_store_dword v86, v62, s[28:29] offset:192 nt
	global_store_dword v87, v51, s[28:29] offset:0 nt
	global_store_dword v87, v55, s[28:29] offset:64 nt
	global_store_dword v87, v59, s[28:29] offset:128 nt
	global_store_dword v87, v63, s[28:29] offset:192 nt
.Lie_nokc_3:
	v_bfe_u32 v88, v48, 16, 1
	v_bfe_u32 v89, v52, 16, 1
	v_bfe_u32 v90, v56, 16, 1
	v_bfe_u32 v91, v60, 16, 1
	v_add3_u32 v48, v48, v88, s33
	v_add3_u32 v52, v52, v89, s33
	v_add3_u32 v56, v56, v90, s33
	v_add3_u32 v60, v60, v91, s33
	v_bfe_u32 v88, v49, 16, 1
	v_bfe_u32 v89, v53, 16, 1
	v_bfe_u32 v90, v57, 16, 1
	v_bfe_u32 v91, v61, 16, 1
	v_add3_u32 v49, v49, v88, s33
	v_add3_u32 v53, v53, v89, s33
	v_add3_u32 v57, v57, v90, s33
	v_add3_u32 v61, v61, v91, s33
	v_bfe_u32 v88, v50, 16, 1
	v_bfe_u32 v89, v54, 16, 1
	v_bfe_u32 v90, v58, 16, 1
	v_bfe_u32 v91, v62, 16, 1
	v_add3_u32 v50, v50, v88, s33
	v_add3_u32 v54, v54, v89, s33
	v_add3_u32 v58, v58, v90, s33
	v_add3_u32 v62, v62, v91, s33
	v_bfe_u32 v88, v51, 16, 1
	v_bfe_u32 v89, v55, 16, 1
	v_bfe_u32 v90, v59, 16, 1
	v_bfe_u32 v91, v63, 16, 1
	v_add3_u32 v51, v51, v88, s33
	v_add3_u32 v55, v55, v89, s33
	v_add3_u32 v59, v59, v90, s33
	v_add3_u32 v63, v63, v91, s33
	s_cmp_eq_u32 s1, 0
	s_cbranch_scc0 .Lie_kst_3
	global_store_short_d16_hi v80, v48, s[34:35] offset:0 nt
	global_store_short_d16_hi v80, v52, s[34:35] offset:32 nt
	global_store_short_d16_hi v80, v56, s[34:35] offset:64 nt
	global_store_short_d16_hi v80, v60, s[34:35] offset:96 nt
	global_store_short_d16_hi v81, v49, s[34:35] offset:0 nt
	global_store_short_d16_hi v81, v53, s[34:35] offset:32 nt
	global_store_short_d16_hi v81, v57, s[34:35] offset:64 nt
	global_store_short_d16_hi v81, v61, s[34:35] offset:96 nt
	global_store_short_d16_hi v82, v50, s[34:35] offset:0 nt
	global_store_short_d16_hi v82, v54, s[34:35] offset:32 nt
	global_store_short_d16_hi v82, v58, s[34:35] offset:64 nt
	global_store_short_d16_hi v82, v62, s[34:35] offset:96 nt
	global_store_short_d16_hi v83, v51, s[34:35] offset:0 nt
	global_store_short_d16_hi v83, v55, s[34:35] offset:32 nt
	global_store_short_d16_hi v83, v59, s[34:35] offset:64 nt
	global_store_short_d16_hi v83, v63, s[34:35] offset:96 nt
	s_branch .Lie_qkn_3
.Lie_kst_3:
	global_store_short_d16_hi v80, v48, s[34:35] offset:0
	global_store_short_d16_hi v80, v52, s[34:35] offset:32
	global_store_short_d16_hi v80, v56, s[34:35] offset:64
	global_store_short_d16_hi v80, v60, s[34:35] offset:96
	global_store_short_d16_hi v81, v49, s[34:35] offset:0
	global_store_short_d16_hi v81, v53, s[34:35] offset:32
	global_store_short_d16_hi v81, v57, s[34:35] offset:64
	global_store_short_d16_hi v81, v61, s[34:35] offset:96
	global_store_short_d16_hi v82, v50, s[34:35] offset:0
	global_store_short_d16_hi v82, v54, s[34:35] offset:32
	global_store_short_d16_hi v82, v58, s[34:35] offset:64
	global_store_short_d16_hi v82, v62, s[34:35] offset:96
	global_store_short_d16_hi v83, v51, s[34:35] offset:0
	global_store_short_d16_hi v83, v55, s[34:35] offset:32
	global_store_short_d16_hi v83, v59, s[34:35] offset:64
	global_store_short_d16_hi v83, v63, s[34:35] offset:96
.Lie_qkn_3:
.Lie_done:
	s_add_i32 s36, s36, s76
	s_cmpk_gt_i32 s36, 0x3bf
	s_cbranch_scc1 .LBB0_1061
.LBB0_442:
	s_mul_hi_i32 s0, s36, 0x2aaaaaab
	s_lshr_b32 s1, s0, 31
	s_ashr_i32 s4, s0, 3
	s_add_i32 s4, s4, s1
	s_waitcnt vmcnt(7)
	v_mov_b32_e32 v16, v127
	s_mul_i32 s0, s4, 48
	s_sub_i32 s0, s36, s0
	v_ashrrev_i32_e32 v17, 6, v16
	s_waitcnt vmcnt(6)
	v_bfe_u32 v20, v16, 3, 3
	v_lshlrev_b32_e32 v21, 3, v17
	s_lshl_b32 s37, s0, 7
	v_lshrrev_b32_e32 v0, 31, v16
	v_or_b32_e32 v8, v21, v20
	v_add_u32_e32 v18, v17, v0
	v_and_b32_e32 v19, 63, v16
	v_add_u32_e32 v0, s37, v8
	v_lshrrev_b32_e32 v22, 1, v8
	v_ashrrev_i32_e32 v1, 31, v0
	v_xor_b32_e32 v2, v22, v16
	v_lshlrev_b32_e32 v96, 10, v17
	v_lshlrev_b32_e32 v97, 4, v19
	v_lshlrev_b64 v[0:1], 11, v[0:1]
	v_lshlrev_b32_e32 v2, 4, v2
	v_add_u32_e32 v10, 32, v8
	v_or_b32_e32 v19, v96, v97
	v_lshl_add_u64 v[0:1], s[30:31], 0, v[0:1]
	v_and_b32_e32 v124, 0x70, v2
	v_add_u32_e32 v2, s37, v10
	v_add_u32_e32 v12, 64, v8
	v_readfirstlane_b32 s0, v19
	v_lshl_add_u64 v[0:1], v[0:1], 0, v[124:125]
	v_ashrrev_i32_e32 v3, 31, v2
	v_add_u32_e32 v4, s37, v12
	v_add_u32_e32 v14, 0x60, v8
	s_mov_b32 m0, s0
	s_lshl_b32 s38, s4, 7
	v_lshlrev_b64 v[2:3], 11, v[2:3]
	v_ashrrev_i32_e32 v5, 31, v4
	v_add_u32_e32 v6, s37, v14
	global_load_lds_dwordx4 v[0:1], off
	v_add_u32_e32 v0, 0x1000, v19
	v_lshl_add_u64 v[2:3], s[30:31], 0, v[2:3]
	v_lshlrev_b64 v[4:5], 11, v[4:5]
	v_ashrrev_i32_e32 v7, 31, v6
	v_add_u32_e32 v8, s38, v8
	v_readfirstlane_b32 s0, v0
	v_add_u32_e32 v0, 0x2000, v19
	v_lshl_add_u64 v[2:3], v[2:3], 0, v[124:125]
	v_lshl_add_u64 v[4:5], s[30:31], 0, v[4:5]
	v_lshlrev_b64 v[6:7], 11, v[6:7]
	v_ashrrev_i32_e32 v9, 31, v8
	v_add_u32_e32 v10, s38, v10
	s_mov_b32 m0, s0
	v_readfirstlane_b32 s0, v0
	v_add_u32_e32 v0, 0x3000, v19
	v_lshl_add_u64 v[4:5], v[4:5], 0, v[124:125]
	v_lshl_add_u64 v[6:7], s[30:31], 0, v[6:7]
	v_lshlrev_b64 v[8:9], 11, v[8:9]
	v_ashrrev_i32_e32 v11, 31, v10
	v_add_u32_e32 v12, s38, v12
	v_add_u32_e32 v23, 0x8000, v19
	global_load_lds_dwordx4 v[2:3], off
	s_mov_b32 m0, s0
	v_readfirstlane_b32 s0, v0
	v_lshl_add_u64 v[6:7], v[6:7], 0, v[124:125]
	v_lshl_add_u64 v[8:9], s[20:21], 0, v[8:9]
	v_lshlrev_b64 v[10:11], 11, v[10:11]
	v_ashrrev_i32_e32 v13, 31, v12
	v_add_u32_e32 v14, s38, v14
	global_load_lds_dwordx4 v[4:5], off
	s_mov_b32 m0, s0
	v_readfirstlane_b32 s0, v23
	v_add_u32_e32 v0, 0x9000, v19
	v_lshl_add_u64 v[8:9], v[8:9], 0, v[124:125]
	v_lshl_add_u64 v[10:11], s[20:21], 0, v[10:11]
	v_lshlrev_b64 v[12:13], 11, v[12:13]
	v_ashrrev_i32_e32 v15, 31, v14
	global_load_lds_dwordx4 v[6:7], off
	s_mov_b32 m0, s0
	v_readfirstlane_b32 s0, v0
	v_add_u32_e32 v0, 0xa000, v19
	v_lshl_add_u64 v[10:11], v[10:11], 0, v[124:125]
	v_lshl_add_u64 v[12:13], s[20:21], 0, v[12:13]
	v_lshlrev_b64 v[14:15], 11, v[14:15]
	global_load_lds_dwordx4 v[8:9], off
	s_mov_b32 m0, s0
	v_readfirstlane_b32 s0, v0
	v_add_u32_e32 v0, 0xb000, v19
	v_lshl_add_u64 v[12:13], v[12:13], 0, v[124:125]
	v_lshl_add_u64 v[14:15], s[20:21], 0, v[14:15]
	global_load_lds_dwordx4 v[10:11], off
	s_mov_b32 m0, s0
	v_readfirstlane_b32 s0, v0
	v_lshl_add_u64 v[14:15], v[14:15], 0, v[124:125]
	global_load_lds_dwordx4 v[12:13], off
	s_mov_b32 m0, s0
	v_and_b32_e32 v109, 31, v16
	global_load_lds_dwordx4 v[14:15], off
	v_and_b32_e32 v0, -2, v18
	v_ashrrev_i32_e32 v108, 1, v18
	s_waitcnt vmcnt(0)
	v_lshrrev_b32_e32 v24, 1, v16
	v_sub_u32_e32 v98, v17, v0
	v_lshlrev_b32_e32 v1, 7, v109
	v_bfe_u32 v110, v16, 5, 1
	v_bfe_u32 v0, v16, 1, 3
	v_lshl_or_b32 v99, v108, 13, v1
	v_lshl_or_b32 v100, v98, 13, v1
	v_bitop3_b32 v1, v110, v24, 7 bitop3:0x78
	v_lshlrev_b32_e32 v101, 4, v1
	v_bitop3_b32 v1, v110, v0, 2 bitop3:0x36
	v_lshlrev_b32_e32 v102, 4, v1
	v_bitop3_b32 v1, v110, v0, 4 bitop3:0x36
	v_bitop3_b32 v0, v110, v0, 6 bitop3:0x36
	v_lshlrev_b32_e32 v104, 4, v0
	v_bitop3_b32 v0, v22, 7, v16 bitop3:0x48
	s_lshl_b32 s0, s36, 7
	v_lshlrev_b32_e32 v124, 4, v0
	v_or_b32_e32 v0, s0, v20
	v_add_u32_e32 v0, v0, v21
	s_mul_i32 s1, s4, 0x1800
	v_subrev_u32_e32 v0, s1, v0
	v_lshlrev_b32_e32 v103, 4, v1
	v_ashrrev_i32_e32 v1, 31, v0
	v_lshlrev_b64 v[0:1], 11, v[0:1]
	v_or_b32_e32 v2, 32, v20
	v_lshl_add_u64 v[64:65], s[10:11], 0, v[0:1]
	v_or_b32_e32 v0, s0, v2
	v_add_u32_e32 v0, v0, v21
	v_subrev_u32_e32 v0, s1, v0
	v_ashrrev_i32_e32 v1, 31, v0
	v_lshlrev_b64 v[0:1], 11, v[0:1]
	v_or_b32_e32 v3, 64, v20
	v_lshl_add_u64 v[66:67], s[10:11], 0, v[0:1]
	v_or_b32_e32 v0, s0, v3
	v_add_u32_e32 v0, v0, v21
	v_subrev_u32_e32 v0, s1, v0
	v_ashrrev_i32_e32 v1, 31, v0
	v_lshlrev_b64 v[0:1], 11, v[0:1]
	v_or_b32_e32 v4, 0x60, v20
	v_lshl_add_u64 v[68:69], s[10:11], 0, v[0:1]
	v_or_b32_e32 v0, s0, v4
	v_add_u32_e32 v0, v0, v21
	v_subrev_u32_e32 v0, s1, v0
	v_ashrrev_i32_e32 v1, 31, v0
	v_lshlrev_b64 v[0:1], 11, v[0:1]
	v_lshl_add_u64 v[70:71], s[10:11], 0, v[0:1]
	v_or_b32_e32 v0, s38, v20
	v_add_u32_e32 v0, v0, v21
	v_ashrrev_i32_e32 v1, 31, v0
	v_lshlrev_b64 v[0:1], 11, v[0:1]
	v_lshl_add_u64 v[72:73], s[10:11], 0, v[0:1]
	v_or_b32_e32 v0, s38, v2
	v_add_u32_e32 v0, v0, v21
	v_ashrrev_i32_e32 v1, 31, v0
	v_lshlrev_b64 v[0:1], 11, v[0:1]
	v_lshl_add_u64 v[74:75], s[10:11], 0, v[0:1]
	v_or_b32_e32 v0, s38, v3
	v_add_u32_e32 v0, v0, v21
	v_ashrrev_i32_e32 v1, 31, v0
	v_lshlrev_b64 v[0:1], 11, v[0:1]
	v_lshl_add_u64 v[76:77], s[10:11], 0, v[0:1]
	v_or_b32_e32 v0, s38, v4
	v_add_u32_e32 v0, v0, v21
	s_waitcnt vmcnt(0)
	v_ashrrev_i32_e32 v1, 31, v0
	v_lshlrev_b64 v[0:1], 11, v[0:1]
	v_mov_b32_e32 v32, 0
	v_lshl_add_u64 v[78:79], s[10:11], 0, v[0:1]
	s_mov_b32 s5, 0
	v_mov_b32_e32 v33, v32
	v_mov_b32_e32 v34, v32
	v_mov_b32_e32 v35, v32
	v_mov_b32_e32 v36, v32
	v_mov_b32_e32 v37, v32
	v_mov_b32_e32 v38, v32
	v_mov_b32_e32 v39, v32
	v_mov_b32_e32 v40, v32
	v_mov_b32_e32 v41, v32
	v_mov_b32_e32 v42, v32
	v_mov_b32_e32 v43, v32
	v_mov_b32_e32 v44, v32
	v_mov_b32_e32 v45, v32
	v_mov_b32_e32 v46, v32
	v_mov_b32_e32 v47, v32
	v_mov_b32_e32 v48, v32
	v_mov_b32_e32 v49, v32
	v_mov_b32_e32 v50, v32
	v_mov_b32_e32 v51, v32
	v_mov_b32_e32 v52, v32
	v_mov_b32_e32 v53, v32
	v_mov_b32_e32 v54, v32
	v_mov_b32_e32 v55, v32
	v_mov_b32_e32 v56, v32
	v_mov_b32_e32 v57, v32
	v_mov_b32_e32 v58, v32
	v_mov_b32_e32 v59, v32
	v_mov_b32_e32 v60, v32
	v_mov_b32_e32 v61, v32
	v_mov_b32_e32 v62, v32
	v_mov_b32_e32 v63, v32
	v_mov_b32_e32 v0, v32
	v_mov_b32_e32 v1, v32
	v_mov_b32_e32 v2, v32
	v_mov_b32_e32 v3, v32
	v_mov_b32_e32 v4, v32
	v_mov_b32_e32 v5, v32
	v_mov_b32_e32 v6, v32
	v_mov_b32_e32 v7, v32
	v_mov_b32_e32 v8, v32
	v_mov_b32_e32 v9, v32
	v_mov_b32_e32 v10, v32
	v_mov_b32_e32 v11, v32
	v_mov_b32_e32 v12, v32
	v_mov_b32_e32 v13, v32
	v_mov_b32_e32 v14, v32
	v_mov_b32_e32 v15, v32
	v_mov_b32_e32 v16, v32
	v_mov_b32_e32 v17, v32
	v_mov_b32_e32 v18, v32
	v_mov_b32_e32 v19, v32
	v_mov_b32_e32 v20, v32
	v_mov_b32_e32 v21, v32
	v_mov_b32_e32 v22, v32
	v_mov_b32_e32 v23, v32
	v_mov_b32_e32 v24, v32
	v_mov_b32_e32 v25, v32
	v_mov_b32_e32 v26, v32
	v_mov_b32_e32 v27, v32
	v_mov_b32_e32 v28, v32
	v_mov_b32_e32 v29, v32
	v_mov_b32_e32 v30, v32
	v_mov_b32_e32 v31, v32
	s_waitcnt lgkmcnt(0)
	s_barrier
	v_or_b32_e32 v116, v96, v97
	s_sub_u32 vcc_lo, s30, s10
	s_subb_u32 vcc_hi, s31, s11
	v_readfirstlane_b32 s101, v116
	s_sub_u32 s0, s20, s10
	s_subb_u32 s1, s21, s11
	v_mov_b32_e32 v116, v124
	v_mov_b32_e32 v117, 0
	v_lshl_add_u64 v[64:65], v[64:65], 0, vcc
	v_lshl_add_u64 v[66:67], v[66:67], 0, vcc
	v_lshl_add_u64 v[68:69], v[68:69], 0, vcc
	v_lshl_add_u64 v[70:71], v[70:71], 0, vcc
	v_lshl_add_u64 v[72:73], v[72:73], 0, s[0:1]
	v_lshl_add_u64 v[74:75], v[74:75], 0, s[0:1]
	v_lshl_add_u64 v[76:77], v[76:77], 0, s[0:1]
	v_lshl_add_u64 v[78:79], v[78:79], 0, s[0:1]
	v_lshl_add_u64 v[64:65], v[64:65], 0, v[116:117]
	v_lshl_add_u64 v[66:67], v[66:67], 0, v[116:117]
	v_lshl_add_u64 v[68:69], v[68:69], 0, v[116:117]
	v_lshl_add_u64 v[70:71], v[70:71], 0, v[116:117]
	v_lshl_add_u64 v[72:73], v[72:73], 0, v[116:117]
	v_lshl_add_u64 v[74:75], v[74:75], 0, v[116:117]
	v_lshl_add_u64 v[76:77], v[76:77], 0, v[116:117]
	v_lshl_add_u64 v[78:79], v[78:79], 0, v[116:117]
	v_and_b32_e32 v118, 15, v127
	v_bfe_u32 v119, v127, 4, 2
	v_bfe_u32 v120, v127, 1, 3
	v_xor_b32_e32 v121, v119, v120
	v_lshlrev_b32_e32 v121, 4, v121
	v_xor_b32_e32 v122, 64, v121
	v_lshrrev_b32_e32 v123, 7, v127
	v_lshl_add_u32 v123, v123, 6, v118
	v_lshlrev_b32_e32 v123, 7, v123
	v_bfe_u32 v116, v127, 6, 1
	v_lshl_add_u32 v116, v116, 6, v118
	v_lshlrev_b32_e32 v116, 7, v116
	v_add_u32_e32 v112, v123, v121
	v_add_u32_e32 v113, v123, v122
	v_add_u32_e32 v114, v116, v121
	v_add_u32_e32 v115, v116, v122
	v_lshl_add_u64 v[64:65], v[64:65], 0, s[2:3]
	v_lshl_add_u64 v[66:67], v[66:67], 0, s[2:3]
	v_lshl_add_u64 v[68:69], v[68:69], 0, s[2:3]
	v_lshl_add_u64 v[70:71], v[70:71], 0, s[2:3]
	v_lshl_add_u64 v[72:73], v[72:73], 0, s[2:3]
	v_lshl_add_u64 v[74:75], v[74:75], 0, s[2:3]
	v_lshl_add_u64 v[76:77], v[76:77], 0, s[2:3]
	v_lshl_add_u64 v[78:79], v[78:79], 0, s[2:3]
	ds_read_b128 v[182:185], v112 offset:0
	ds_read_b128 v[198:201], v114 offset:32768
	ds_read_b128 v[202:205], v114 offset:34816
	ds_read_b128 v[206:209], v114 offset:36864
	ds_read_b128 v[210:213], v114 offset:38912
	ds_read_b128 v[186:189], v112 offset:2048
	ds_read_b128 v[190:193], v112 offset:4096
	ds_read_b128 v[194:197], v112 offset:6144
	s_add_u32 m0, s101, 0x4000
	s_nop 0
	global_load_lds_dwordx4 v[64:65], off
	v_lshl_add_u64 v[64:65], v[64:65], 0, s[2:3]
	s_add_u32 m0, s101, 0x5000
	s_nop 0
	global_load_lds_dwordx4 v[66:67], off
	v_lshl_add_u64 v[66:67], v[66:67], 0, s[2:3]
	s_add_u32 m0, s101, 0x6000
	s_nop 0
	global_load_lds_dwordx4 v[68:69], off
	v_lshl_add_u64 v[68:69], v[68:69], 0, s[2:3]
	s_add_u32 m0, s101, 0x7000
	s_nop 0
	global_load_lds_dwordx4 v[70:71], off
	v_lshl_add_u64 v[70:71], v[70:71], 0, s[2:3]
	s_mov_b32 s100, 7
.Linp_loop:
	s_waitcnt lgkmcnt(6)
	v_mfma_f32_16x16x32_bf16 v[0:3], v[182:185], v[198:201], v[0:3]
	s_add_u32 m0, s101, 0xc000
	ds_read_b128 v[80:83], v113 offset:0
	global_load_lds_dwordx4 v[72:73], off
	v_lshl_add_u64 v[72:73], v[72:73], 0, s[2:3]
	s_waitcnt lgkmcnt(6)
	v_mfma_f32_16x16x32_bf16 v[4:7], v[182:185], v[202:205], v[4:7]
	s_add_u32 m0, s101, 0xd000
	ds_read_b128 v[96:99], v115 offset:32768
	global_load_lds_dwordx4 v[74:75], off
	v_lshl_add_u64 v[74:75], v[74:75], 0, s[2:3]
	s_waitcnt lgkmcnt(6)
	v_mfma_f32_16x16x32_bf16 v[8:11], v[182:185], v[206:209], v[8:11]
	s_add_u32 m0, s101, 0xe000
	ds_read_b128 v[100:103], v115 offset:34816
	global_load_lds_dwordx4 v[76:77], off
	v_lshl_add_u64 v[76:77], v[76:77], 0, s[2:3]
	s_waitcnt lgkmcnt(6)
	v_mfma_f32_16x16x32_bf16 v[12:15], v[182:185], v[210:213], v[12:15]
	s_add_u32 m0, s101, 0xf000
	ds_read_b128 v[104:107], v115 offset:36864
	global_load_lds_dwordx4 v[78:79], off
	v_lshl_add_u64 v[78:79], v[78:79], 0, s[2:3]
	s_waitcnt lgkmcnt(6)
	v_mfma_f32_16x16x32_bf16 v[16:19], v[186:189], v[198:201], v[16:19]
	ds_read_b128 v[108:111], v115 offset:38912
	v_mfma_f32_16x16x32_bf16 v[20:23], v[186:189], v[202:205], v[20:23]
	ds_read_b128 v[84:87], v113 offset:2048
	v_mfma_f32_16x16x32_bf16 v[24:27], v[186:189], v[206:209], v[24:27]
	ds_read_b128 v[88:91], v113 offset:4096
	v_mfma_f32_16x16x32_bf16 v[28:31], v[186:189], v[210:213], v[28:31]
	ds_read_b128 v[92:95], v113 offset:6144
	s_waitcnt lgkmcnt(9)
	v_mfma_f32_16x16x32_bf16 v[32:35], v[190:193], v[198:201], v[32:35]
	v_mfma_f32_16x16x32_bf16 v[36:39], v[190:193], v[202:205], v[36:39]
	v_mfma_f32_16x16x32_bf16 v[40:43], v[190:193], v[206:209], v[40:43]
	v_mfma_f32_16x16x32_bf16 v[44:47], v[190:193], v[210:213], v[44:47]
	s_waitcnt lgkmcnt(8)
	v_mfma_f32_16x16x32_bf16 v[48:51], v[194:197], v[198:201], v[48:51]
	v_mfma_f32_16x16x32_bf16 v[52:55], v[194:197], v[202:205], v[52:55]
	v_mfma_f32_16x16x32_bf16 v[56:59], v[194:197], v[206:209], v[56:59]
	v_mfma_f32_16x16x32_bf16 v[60:63], v[194:197], v[210:213], v[60:63]
	s_waitcnt vmcnt(0) lgkmcnt(0)
	s_barrier
	s_setprio 2
	v_mfma_f32_16x16x32_bf16 v[0:3], v[80:83], v[96:99], v[0:3]
	s_add_u32 m0, s101, 0x0
	ds_read_b128 v[182:185], v112 offset:16384
	global_load_lds_dwordx4 v[64:65], off
	v_lshl_add_u64 v[64:65], v[64:65], 0, s[2:3]
	v_mfma_f32_16x16x32_bf16 v[4:7], v[80:83], v[100:103], v[4:7]
	s_add_u32 m0, s101, 0x1000
	ds_read_b128 v[198:201], v114 offset:49152
	global_load_lds_dwordx4 v[66:67], off
	v_lshl_add_u64 v[66:67], v[66:67], 0, s[2:3]
	v_mfma_f32_16x16x32_bf16 v[8:11], v[80:83], v[104:107], v[8:11]
	s_add_u32 m0, s101, 0x2000
	ds_read_b128 v[202:205], v114 offset:51200
	global_load_lds_dwordx4 v[68:69], off
	v_lshl_add_u64 v[68:69], v[68:69], 0, s[2:3]
	v_mfma_f32_16x16x32_bf16 v[12:15], v[80:83], v[108:111], v[12:15]
	s_add_u32 m0, s101, 0x3000
	ds_read_b128 v[206:209], v114 offset:53248
	global_load_lds_dwordx4 v[70:71], off
	v_lshl_add_u64 v[70:71], v[70:71], 0, s[2:3]
	v_mfma_f32_16x16x32_bf16 v[16:19], v[84:87], v[96:99], v[16:19]
	ds_read_b128 v[210:213], v114 offset:55296
	v_mfma_f32_16x16x32_bf16 v[20:23], v[84:87], v[100:103], v[20:23]
	ds_read_b128 v[186:189], v112 offset:18432
	v_mfma_f32_16x16x32_bf16 v[24:27], v[84:87], v[104:107], v[24:27]
	ds_read_b128 v[190:193], v112 offset:20480
	v_mfma_f32_16x16x32_bf16 v[28:31], v[84:87], v[108:111], v[28:31]
	ds_read_b128 v[194:197], v112 offset:22528
	v_mfma_f32_16x16x32_bf16 v[32:35], v[88:91], v[96:99], v[32:35]
	v_mfma_f32_16x16x32_bf16 v[36:39], v[88:91], v[100:103], v[36:39]
	v_mfma_f32_16x16x32_bf16 v[40:43], v[88:91], v[104:107], v[40:43]
	v_mfma_f32_16x16x32_bf16 v[44:47], v[88:91], v[108:111], v[44:47]
	v_mfma_f32_16x16x32_bf16 v[48:51], v[92:95], v[96:99], v[48:51]
	v_mfma_f32_16x16x32_bf16 v[52:55], v[92:95], v[100:103], v[52:55]
	v_mfma_f32_16x16x32_bf16 v[56:59], v[92:95], v[104:107], v[56:59]
	v_mfma_f32_16x16x32_bf16 v[60:63], v[92:95], v[108:111], v[60:63]
	s_setprio 0
	s_waitcnt lgkmcnt(6)
	v_mfma_f32_16x16x32_bf16 v[0:3], v[182:185], v[198:201], v[0:3]
	s_add_u32 m0, s101, 0x8000
	ds_read_b128 v[80:83], v113 offset:16384
	global_load_lds_dwordx4 v[72:73], off
	v_lshl_add_u64 v[72:73], v[72:73], 0, s[2:3]
	s_waitcnt lgkmcnt(6)
	v_mfma_f32_16x16x32_bf16 v[4:7], v[182:185], v[202:205], v[4:7]
	s_add_u32 m0, s101, 0x9000
	ds_read_b128 v[96:99], v115 offset:49152
	global_load_lds_dwordx4 v[74:75], off
	v_lshl_add_u64 v[74:75], v[74:75], 0, s[2:3]
	s_waitcnt lgkmcnt(6)
	v_mfma_f32_16x16x32_bf16 v[8:11], v[182:185], v[206:209], v[8:11]
	s_add_u32 m0, s101, 0xa000
	ds_read_b128 v[100:103], v115 offset:51200
	global_load_lds_dwordx4 v[76:77], off
	v_lshl_add_u64 v[76:77], v[76:77], 0, s[2:3]
	s_waitcnt lgkmcnt(6)
	v_mfma_f32_16x16x32_bf16 v[12:15], v[182:185], v[210:213], v[12:15]
	s_add_u32 m0, s101, 0xb000
	ds_read_b128 v[104:107], v115 offset:53248
	global_load_lds_dwordx4 v[78:79], off
	v_lshl_add_u64 v[78:79], v[78:79], 0, s[2:3]
	s_waitcnt lgkmcnt(6)
	v_mfma_f32_16x16x32_bf16 v[16:19], v[186:189], v[198:201], v[16:19]
	ds_read_b128 v[108:111], v115 offset:55296
	v_mfma_f32_16x16x32_bf16 v[20:23], v[186:189], v[202:205], v[20:23]
	ds_read_b128 v[84:87], v113 offset:18432
	v_mfma_f32_16x16x32_bf16 v[24:27], v[186:189], v[206:209], v[24:27]
	ds_read_b128 v[88:91], v113 offset:20480
	v_mfma_f32_16x16x32_bf16 v[28:31], v[186:189], v[210:213], v[28:31]
	ds_read_b128 v[92:95], v113 offset:22528
	s_waitcnt lgkmcnt(9)
	v_mfma_f32_16x16x32_bf16 v[32:35], v[190:193], v[198:201], v[32:35]
	v_mfma_f32_16x16x32_bf16 v[36:39], v[190:193], v[202:205], v[36:39]
	v_mfma_f32_16x16x32_bf16 v[40:43], v[190:193], v[206:209], v[40:43]
	v_mfma_f32_16x16x32_bf16 v[44:47], v[190:193], v[210:213], v[44:47]
	s_waitcnt lgkmcnt(8)
	v_mfma_f32_16x16x32_bf16 v[48:51], v[194:197], v[198:201], v[48:51]
	v_mfma_f32_16x16x32_bf16 v[52:55], v[194:197], v[202:205], v[52:55]
	v_mfma_f32_16x16x32_bf16 v[56:59], v[194:197], v[206:209], v[56:59]
	v_mfma_f32_16x16x32_bf16 v[60:63], v[194:197], v[210:213], v[60:63]
	s_waitcnt vmcnt(0) lgkmcnt(0)
	s_barrier
	s_setprio 2
	v_mfma_f32_16x16x32_bf16 v[0:3], v[80:83], v[96:99], v[0:3]
	s_add_u32 m0, s101, 0x4000
	ds_read_b128 v[182:185], v112 offset:0
	global_load_lds_dwordx4 v[64:65], off
	v_lshl_add_u64 v[64:65], v[64:65], 0, s[2:3]
	v_mfma_f32_16x16x32_bf16 v[4:7], v[80:83], v[100:103], v[4:7]
	s_add_u32 m0, s101, 0x5000
	ds_read_b128 v[198:201], v114 offset:32768
	global_load_lds_dwordx4 v[66:67], off
	v_lshl_add_u64 v[66:67], v[66:67], 0, s[2:3]
	v_mfma_f32_16x16x32_bf16 v[8:11], v[80:83], v[104:107], v[8:11]
	s_add_u32 m0, s101, 0x6000
	ds_read_b128 v[202:205], v114 offset:34816
	global_load_lds_dwordx4 v[68:69], off
	v_lshl_add_u64 v[68:69], v[68:69], 0, s[2:3]
	v_mfma_f32_16x16x32_bf16 v[12:15], v[80:83], v[108:111], v[12:15]
	s_add_u32 m0, s101, 0x7000
	ds_read_b128 v[206:209], v114 offset:36864
	global_load_lds_dwordx4 v[70:71], off
	v_lshl_add_u64 v[70:71], v[70:71], 0, s[2:3]
	v_mfma_f32_16x16x32_bf16 v[16:19], v[84:87], v[96:99], v[16:19]
	ds_read_b128 v[210:213], v114 offset:38912
	v_mfma_f32_16x16x32_bf16 v[20:23], v[84:87], v[100:103], v[20:23]
	ds_read_b128 v[186:189], v112 offset:2048
	v_mfma_f32_16x16x32_bf16 v[24:27], v[84:87], v[104:107], v[24:27]
	ds_read_b128 v[190:193], v112 offset:4096
	v_mfma_f32_16x16x32_bf16 v[28:31], v[84:87], v[108:111], v[28:31]
	ds_read_b128 v[194:197], v112 offset:6144
	v_mfma_f32_16x16x32_bf16 v[32:35], v[88:91], v[96:99], v[32:35]
	v_mfma_f32_16x16x32_bf16 v[36:39], v[88:91], v[100:103], v[36:39]
	v_mfma_f32_16x16x32_bf16 v[40:43], v[88:91], v[104:107], v[40:43]
	v_mfma_f32_16x16x32_bf16 v[44:47], v[88:91], v[108:111], v[44:47]
	v_mfma_f32_16x16x32_bf16 v[48:51], v[92:95], v[96:99], v[48:51]
	v_mfma_f32_16x16x32_bf16 v[52:55], v[92:95], v[100:103], v[52:55]
	v_mfma_f32_16x16x32_bf16 v[56:59], v[92:95], v[104:107], v[56:59]
	v_mfma_f32_16x16x32_bf16 v[60:63], v[92:95], v[108:111], v[60:63]
	s_setprio 0
	s_add_i32 s100, s100, -1
	s_cmp_lg_u32 s100, 0
	s_cbranch_scc1 .Linp_loop
	s_waitcnt lgkmcnt(6)
	v_mfma_f32_16x16x32_bf16 v[0:3], v[182:185], v[198:201], v[0:3]
	s_add_u32 m0, s101, 0xc000
	ds_read_b128 v[80:83], v113 offset:0
	global_load_lds_dwordx4 v[72:73], off
	v_lshl_add_u64 v[72:73], v[72:73], 0, s[2:3]
	s_waitcnt lgkmcnt(6)
	v_mfma_f32_16x16x32_bf16 v[4:7], v[182:185], v[202:205], v[4:7]
	s_add_u32 m0, s101, 0xd000
	ds_read_b128 v[96:99], v115 offset:32768
	global_load_lds_dwordx4 v[74:75], off
	v_lshl_add_u64 v[74:75], v[74:75], 0, s[2:3]
	s_waitcnt lgkmcnt(6)
	v_mfma_f32_16x16x32_bf16 v[8:11], v[182:185], v[206:209], v[8:11]
	s_add_u32 m0, s101, 0xe000
	ds_read_b128 v[100:103], v115 offset:34816
	global_load_lds_dwordx4 v[76:77], off
	v_lshl_add_u64 v[76:77], v[76:77], 0, s[2:3]
	s_waitcnt lgkmcnt(6)
	v_mfma_f32_16x16x32_bf16 v[12:15], v[182:185], v[210:213], v[12:15]
	s_add_u32 m0, s101, 0xf000
	ds_read_b128 v[104:107], v115 offset:36864
	global_load_lds_dwordx4 v[78:79], off
	v_lshl_add_u64 v[78:79], v[78:79], 0, s[2:3]
	s_waitcnt lgkmcnt(6)
	v_mfma_f32_16x16x32_bf16 v[16:19], v[186:189], v[198:201], v[16:19]
	ds_read_b128 v[108:111], v115 offset:38912
	v_mfma_f32_16x16x32_bf16 v[20:23], v[186:189], v[202:205], v[20:23]
	ds_read_b128 v[84:87], v113 offset:2048
	v_mfma_f32_16x16x32_bf16 v[24:27], v[186:189], v[206:209], v[24:27]
	ds_read_b128 v[88:91], v113 offset:4096
	v_mfma_f32_16x16x32_bf16 v[28:31], v[186:189], v[210:213], v[28:31]
	ds_read_b128 v[92:95], v113 offset:6144
	s_waitcnt lgkmcnt(9)
	v_mfma_f32_16x16x32_bf16 v[32:35], v[190:193], v[198:201], v[32:35]
	v_mfma_f32_16x16x32_bf16 v[36:39], v[190:193], v[202:205], v[36:39]
	v_mfma_f32_16x16x32_bf16 v[40:43], v[190:193], v[206:209], v[40:43]
	v_mfma_f32_16x16x32_bf16 v[44:47], v[190:193], v[210:213], v[44:47]
	s_waitcnt lgkmcnt(8)
	v_mfma_f32_16x16x32_bf16 v[48:51], v[194:197], v[198:201], v[48:51]
	v_mfma_f32_16x16x32_bf16 v[52:55], v[194:197], v[202:205], v[52:55]
	v_mfma_f32_16x16x32_bf16 v[56:59], v[194:197], v[206:209], v[56:59]
	v_mfma_f32_16x16x32_bf16 v[60:63], v[194:197], v[210:213], v[60:63]
	s_waitcnt vmcnt(0) lgkmcnt(0)
	s_barrier
	v_mfma_f32_16x16x32_bf16 v[0:3], v[80:83], v[96:99], v[0:3]
	ds_read_b128 v[182:185], v112 offset:16384
	v_mfma_f32_16x16x32_bf16 v[4:7], v[80:83], v[100:103], v[4:7]
	ds_read_b128 v[198:201], v114 offset:49152
	v_mfma_f32_16x16x32_bf16 v[8:11], v[80:83], v[104:107], v[8:11]
	ds_read_b128 v[202:205], v114 offset:51200
	v_mfma_f32_16x16x32_bf16 v[12:15], v[80:83], v[108:111], v[12:15]
	ds_read_b128 v[206:209], v114 offset:53248
	v_mfma_f32_16x16x32_bf16 v[16:19], v[84:87], v[96:99], v[16:19]
	ds_read_b128 v[210:213], v114 offset:55296
	v_mfma_f32_16x16x32_bf16 v[20:23], v[84:87], v[100:103], v[20:23]
	ds_read_b128 v[186:189], v112 offset:18432
	v_mfma_f32_16x16x32_bf16 v[24:27], v[84:87], v[104:107], v[24:27]
	ds_read_b128 v[190:193], v112 offset:20480
	v_mfma_f32_16x16x32_bf16 v[28:31], v[84:87], v[108:111], v[28:31]
	ds_read_b128 v[194:197], v112 offset:22528
	v_mfma_f32_16x16x32_bf16 v[32:35], v[88:91], v[96:99], v[32:35]
	v_mfma_f32_16x16x32_bf16 v[36:39], v[88:91], v[100:103], v[36:39]
	v_mfma_f32_16x16x32_bf16 v[40:43], v[88:91], v[104:107], v[40:43]
	v_mfma_f32_16x16x32_bf16 v[44:47], v[88:91], v[108:111], v[44:47]
	v_mfma_f32_16x16x32_bf16 v[48:51], v[92:95], v[96:99], v[48:51]
	v_mfma_f32_16x16x32_bf16 v[52:55], v[92:95], v[100:103], v[52:55]
	v_mfma_f32_16x16x32_bf16 v[56:59], v[92:95], v[104:107], v[56:59]
	v_mfma_f32_16x16x32_bf16 v[60:63], v[92:95], v[108:111], v[60:63]
	s_waitcnt lgkmcnt(6)
	v_mfma_f32_16x16x32_bf16 v[0:3], v[182:185], v[198:201], v[0:3]
	ds_read_b128 v[80:83], v113 offset:16384
	s_waitcnt lgkmcnt(6)
	v_mfma_f32_16x16x32_bf16 v[4:7], v[182:185], v[202:205], v[4:7]
	ds_read_b128 v[96:99], v115 offset:49152
	s_waitcnt lgkmcnt(6)
	v_mfma_f32_16x16x32_bf16 v[8:11], v[182:185], v[206:209], v[8:11]
	ds_read_b128 v[100:103], v115 offset:51200
	s_waitcnt lgkmcnt(6)
	v_mfma_f32_16x16x32_bf16 v[12:15], v[182:185], v[210:213], v[12:15]
	ds_read_b128 v[104:107], v115 offset:53248
	s_waitcnt lgkmcnt(6)
	v_mfma_f32_16x16x32_bf16 v[16:19], v[186:189], v[198:201], v[16:19]
	ds_read_b128 v[108:111], v115 offset:55296
	v_mfma_f32_16x16x32_bf16 v[20:23], v[186:189], v[202:205], v[20:23]
	ds_read_b128 v[84:87], v113 offset:18432
	v_mfma_f32_16x16x32_bf16 v[24:27], v[186:189], v[206:209], v[24:27]
	ds_read_b128 v[88:91], v113 offset:20480
	v_mfma_f32_16x16x32_bf16 v[28:31], v[186:189], v[210:213], v[28:31]
	ds_read_b128 v[92:95], v113 offset:22528
	s_waitcnt lgkmcnt(9)
	v_mfma_f32_16x16x32_bf16 v[32:35], v[190:193], v[198:201], v[32:35]
	v_mfma_f32_16x16x32_bf16 v[36:39], v[190:193], v[202:205], v[36:39]
	v_mfma_f32_16x16x32_bf16 v[40:43], v[190:193], v[206:209], v[40:43]
	v_mfma_f32_16x16x32_bf16 v[44:47], v[190:193], v[210:213], v[44:47]
	s_waitcnt lgkmcnt(8)
	v_mfma_f32_16x16x32_bf16 v[48:51], v[194:197], v[198:201], v[48:51]
	v_mfma_f32_16x16x32_bf16 v[52:55], v[194:197], v[202:205], v[52:55]
	v_mfma_f32_16x16x32_bf16 v[56:59], v[194:197], v[206:209], v[56:59]
	v_mfma_f32_16x16x32_bf16 v[60:63], v[194:197], v[210:213], v[60:63]
	s_waitcnt vmcnt(0) lgkmcnt(0)
	s_barrier
	v_mfma_f32_16x16x32_bf16 v[0:3], v[80:83], v[96:99], v[0:3]
	v_mfma_f32_16x16x32_bf16 v[4:7], v[80:83], v[100:103], v[4:7]
	v_mfma_f32_16x16x32_bf16 v[8:11], v[80:83], v[104:107], v[8:11]
	v_mfma_f32_16x16x32_bf16 v[12:15], v[80:83], v[108:111], v[12:15]
	v_mfma_f32_16x16x32_bf16 v[16:19], v[84:87], v[96:99], v[16:19]
	v_mfma_f32_16x16x32_bf16 v[20:23], v[84:87], v[100:103], v[20:23]
	v_mfma_f32_16x16x32_bf16 v[24:27], v[84:87], v[104:107], v[24:27]
	v_mfma_f32_16x16x32_bf16 v[28:31], v[84:87], v[108:111], v[28:31]
	v_mfma_f32_16x16x32_bf16 v[32:35], v[88:91], v[96:99], v[32:35]
	v_mfma_f32_16x16x32_bf16 v[36:39], v[88:91], v[100:103], v[36:39]
	v_mfma_f32_16x16x32_bf16 v[40:43], v[88:91], v[104:107], v[40:43]
	v_mfma_f32_16x16x32_bf16 v[44:47], v[88:91], v[108:111], v[44:47]
	v_mfma_f32_16x16x32_bf16 v[48:51], v[92:95], v[96:99], v[48:51]
	v_mfma_f32_16x16x32_bf16 v[52:55], v[92:95], v[100:103], v[52:55]
	v_mfma_f32_16x16x32_bf16 v[56:59], v[92:95], v[104:107], v[56:59]
	v_mfma_f32_16x16x32_bf16 v[60:63], v[92:95], v[108:111], v[60:63]
	s_nop 7
	s_nop 7
	s_branch .Linp_epi
